# GEMM mainloops (fold, in-proj, out-proj): all s_setprio removed (hipcc per-cluster priority flips), on top of v8
# speedup vs baseline: 1.0091x; 1.0091x over previous
; #define PG8_STAGE(bufoff, gbase, voff) do { _Pragma("unroll") for (int _i = 0; _i < 2; ++_i) \
;         __builtin_amdgcn_global_load_lds((const unsigned*)((const char*)(gbase) + (voff)[_i]), (LAS unsigned*)(lds + (bufoff) + ldsw + _i * 8192), 16, 0, 0); } while (0)
; #define PG8_LDA(dst, b, h) do { _Pragma("unroll") for (int m = 0; m < 4; ++m) _Pragma("unroll") for (int k = 0; k < 2; ++k) dst[m][k] = *(const LAS bf16x8*)(lds + PG8_SA(b, h) + aoff + m * 2048 + k * 1024); } while (0)
; #define PG8_LDB(dst, b, h) do { _Pragma("unroll") for (int n = 0; n < 2; ++n) _Pragma("unroll") for (int k = 0; k < 2; ++k) dst[n][k] = *(const LAS bf16x8*)(lds + PG8_SB(b, h) + boff + n * 2048 + k * 1024); } while (0)
; #define PG8_WAIT_V(n) asm volatile("s_waitcnt vmcnt(" #n ")" ::: "memory")
; #define PG8_WAIT_L(n) asm volatile("s_waitcnt lgkmcnt(" #n ")" ::: "memory")
; #define PG8_BAR __builtin_amdgcn_s_barrier()
; #define PG8_SCHED __builtin_amdgcn_sched_barrier(0)
; template <class Epi, class Sched>
; DI void gemm_phase(LAS unsigned char* lds, const Gemm g, const Sched& S, const Epi& E) {
;     ...
;     const char* cA = S.aptr(cur); const char* cB = S.bptr(cur);
;     PG8_STAGE(PG8_SB(0, 0), cB, voffB); PG8_STAGE(PG8_SB(0, 1), cB + hstepB, voffB); PG8_STAGE(PG8_SA(0, 0), cA, voffA); PG8_STAGE(PG8_SA(0, 1), cA + hstepA, voffA);
;     if (wr == 1) PG8_BAR;
;     PG8_WAIT_V(2); PG8_BAR;
;     PG8_STAGE(PG8_SB(1, 0), cB + kstep, voffB); PG8_STAGE(PG8_SA(1, 0), cA + kstep, voffA); PG8_STAGE(PG8_SB(1, 1), cB + hstepB + kstep, voffB);
;     PG8_WAIT_V(6); PG8_BAR;
;     for (;;) {
;         const bool has_next = S.next(ui + 1, nxt);
;         const char* nA = has_next ? S.aptr(nxt) : cA; const char* nB = has_next ? S.bptr(nxt) : cB;
;         for (int t = 0; t < nt; t += 2) {
;             const bool last = (t == nt - 2);
;             const char* a1 = cA + (size_t)(t + 1) * kstep;
;             const char* a2 = last ? nA : cA + (size_t)(t + 2) * kstep; const char* b2 = last ? nB : cB + (size_t)(t + 2) * kstep;
;             const char* a3 = a2 + kstep; const char* b3 = b2 + kstep;
;             PG8_LDB(B0, 0, 0); PG8_LDB(B1, 0, 1); PG8_SCHED; PG8_LDA(At, 0, 0); PG8_STAGE(PG8_SA(1, 1), a1 + hstepA, voffA);
;             PG8_WAIT_V(8); PG8_WAIT_L(0); PG8_BAR; PG8_MMA(0, 0, At, B0); PG8_MMA(0, 1, At, B1); PG8_BAR; PG8_SCHED;
.LBB0_120:
	s_lshl_b32 s1, s14, 5
	s_add_i32 s29, 0, 0x18000
	s_and_b32 s1, s1, 0x60
	s_add_i32 s3, s29, s8
	s_mov_b64 s[10:11], 0x80
	s_lshl_b32 s15, s9, 13
	s_lshl_b32 s14, s1, 7
	v_lshl_add_u64 v[2:3], v[28:29], 0, s[10:11]
	s_mov_b32 m0, s3
	s_add_i32 s20, s3, 0x2000
	s_add_i32 s5, s28, 0x8000
	s_add_i32 s21, s28, 0xa000
	s_waitcnt vmcnt(2)
	s_barrier
	global_load_lds_dwordx4 v[2:3], off
	v_lshl_add_u64 v[4:5], v[30:31], 0, s[10:11]
	s_mov_b32 m0, s20
	v_lshl_add_u64 v[0:1], v[22:23], 0, s[10:11]
	v_lshl_add_u64 v[6:7], v[24:25], 0, s[10:11]
	s_add_u32 s10, s6, 0x40080
	global_load_lds_dwordx4 v[4:5], off
	s_mov_b32 m0, s5
	s_addc_u32 s11, s7, 0
	s_add_i32 s30, 0, 0x1c000
	global_load_lds_dwordx4 v[0:1], off
	s_mov_b32 m0, s21
	s_add_i32 s24, s30, s8
	global_load_lds_dwordx4 v[6:7], off
	v_lshl_add_u64 v[8:9], s[10:11], 0, v[34:35]
	s_mov_b32 m0, s24
	s_add_i32 s25, s24, 0x2000
	global_load_lds_dwordx4 v[8:9], off
	v_lshl_add_u64 v[10:11], s[10:11], 0, v[32:33]
	s_mov_b32 m0, s25
	v_bfe_u32 v128, v36, 4, 2
	global_load_lds_dwordx4 v[10:11], off
	v_and_b32_e32 v37, 15, v36
	v_lshlrev_b32_e32 v38, 4, v128
	v_lshlrev_b32_e32 v36, 2, v36
	v_lshl_or_b32 v129, s9, 6, v37
	v_lshl_or_b32 v37, v37, 6, v38
	v_and_b32_e32 v36, 32, v36
	v_bitop3_b32 v38, v37, s15, v36 bitop3:0xde
	v_bitop3_b32 v36, v37, s14, v36 bitop3:0xde
	s_add_i32 s9, 0, 0x10000
	s_add_i32 s33, 0, 0x14000
	v_add_u32_e32 v221, s9, v36
	s_add_u32 s38, s12, 0x10080
	s_waitcnt vmcnt(6)
	s_barrier
	v_add_u32_e32 v234, s33, v36
	v_add_u32_e32 v246, 0, v38
	v_add_u32_e32 v235, s29, v36
	v_add_u32_e32 v236, s30, v36
	s_addc_u32 s39, s13, 0
	s_add_i32 s30, s9, s8
	ds_read_b128 v[36:39], v221
	ds_read_b128 v[40:43], v221 offset:1024
	ds_read_b128 v[44:47], v221 offset:2048
	ds_read_b128 v[48:51], v221 offset:3072
	ds_read_b128 v[52:55], v234
	ds_read_b128 v[56:59], v234 offset:1024
	ds_read_b128 v[60:63], v234 offset:2048
	ds_read_b128 v[64:67], v234 offset:3072
	s_add_i32 s35, s28, 0xc000
	s_add_i32 s34, s28, 0xe000
	s_add_i32 s29, s30, 0x2000
	s_add_u32 s14, s6, 0x40100
	s_addc_u32 s15, s7, 0
	s_add_i32 s33, s33, s8
	s_add_i32 s31, s33, 0x2000
	s_add_u32 s10, s12, 0x10100
	s_addc_u32 s11, s13, 0
	s_add_u32 s8, s6, 0x40180
	s_addc_u32 s9, s7, 0
	s_add_u32 s6, s12, 0x10180
	s_addc_u32 s7, s13, 0
	s_cmpk_gt_u32 s36, 0xff
	s_mov_b32 m0, s35
	v_lshl_add_u64 v[100:101], s[38:39], 0, v[18:19]
	ds_read_b128 v[68:71], v246
	ds_read_b128 v[72:75], v246 offset:1024
	ds_read_b128 v[76:79], v246 offset:2048
	ds_read_b128 v[80:83], v246 offset:3072
	ds_read_b128 v[84:87], v246 offset:4096
	ds_read_b128 v[88:91], v246 offset:5120
	ds_read_b128 v[92:95], v246 offset:6144
	ds_read_b128 v[96:99], v246 offset:7168
	global_load_lds_dwordx4 v[100:101], off
	v_lshl_add_u64 v[100:101], s[38:39], 0, v[16:17]
	s_mov_b32 m0, s34
	s_nop 0
	global_load_lds_dwordx4 v[100:101], off
	s_waitcnt vmcnt(8)
	s_waitcnt lgkmcnt(0)
	s_barrier
	s_waitcnt lgkmcnt(0)
	v_mfma_f32_16x16x32_bf16 v[100:103], v[36:39], v[68:71], 0
	v_mfma_f32_16x16x32_bf16 v[104:107], v[44:47], v[68:71], 0
	v_mfma_f32_16x16x32_bf16 v[108:111], v[36:39], v[76:79], 0
	v_mfma_f32_16x16x32_bf16 v[112:115], v[44:47], v[76:79], 0
	v_mfma_f32_16x16x32_bf16 v[116:119], v[36:39], v[84:87], 0
	v_mfma_f32_16x16x32_bf16 v[120:123], v[44:47], v[84:87], 0
	v_mfma_f32_16x16x32_bf16 v[124:127], v[36:39], v[92:95], 0
	v_mfma_f32_16x16x32_bf16 v[100:103], v[40:43], v[72:75], v[100:103]
	v_mfma_f32_16x16x32_bf16 v[104:107], v[48:51], v[72:75], v[104:107]
	v_mfma_f32_16x16x32_bf16 v[108:111], v[40:43], v[80:83], v[108:111]
	v_mfma_f32_16x16x32_bf16 v[112:115], v[48:51], v[80:83], v[112:115]
	v_mfma_f32_16x16x32_bf16 v[116:119], v[40:43], v[88:91], v[116:119]
	v_mfma_f32_16x16x32_bf16 v[120:123], v[48:51], v[88:91], v[120:123]
	v_mfma_f32_16x16x32_bf16 v[124:127], v[40:43], v[96:99], v[124:127]
	v_mfma_f32_16x16x32_bf16 v[130:133], v[44:47], v[92:95], 0
	v_mfma_f32_16x16x32_bf16 v[130:133], v[48:51], v[96:99], v[130:133]
	v_mfma_f32_16x16x32_bf16 v[134:137], v[52:55], v[68:71], 0
	v_mfma_f32_16x16x32_bf16 v[68:71], v[60:63], v[68:71], 0
	v_mfma_f32_16x16x32_bf16 v[134:137], v[56:59], v[72:75], v[134:137]
	v_mfma_f32_16x16x32_bf16 v[68:71], v[64:67], v[72:75], v[68:71]
	v_mfma_f32_16x16x32_bf16 v[72:75], v[52:55], v[76:79], 0
	v_mfma_f32_16x16x32_bf16 v[76:79], v[60:63], v[76:79], 0
	v_mfma_f32_16x16x32_bf16 v[72:75], v[56:59], v[80:83], v[72:75]
	v_mfma_f32_16x16x32_bf16 v[76:79], v[64:67], v[80:83], v[76:79]
	v_mfma_f32_16x16x32_bf16 v[80:83], v[52:55], v[84:87], 0
	v_mfma_f32_16x16x32_bf16 v[84:87], v[60:63], v[84:87], 0
	v_mfma_f32_16x16x32_bf16 v[80:83], v[56:59], v[88:91], v[80:83]
	v_mfma_f32_16x16x32_bf16 v[84:87], v[64:67], v[88:91], v[84:87]
	v_mfma_f32_16x16x32_bf16 v[88:91], v[52:55], v[92:95], 0
	v_mfma_f32_16x16x32_bf16 v[92:95], v[60:63], v[92:95], 0
	v_mfma_f32_16x16x32_bf16 v[88:91], v[56:59], v[96:99], v[88:91]
	v_mfma_f32_16x16x32_bf16 v[92:95], v[64:67], v[96:99], v[92:95]
	s_barrier
	s_mov_b64 s[12:13], 0x100
	s_mov_b32 m0, s30
	v_lshl_add_u64 v[166:167], v[28:29], 0, s[12:13]
	ds_read_b128 v[96:99], v246 offset:16384
	ds_read_b128 v[138:141], v246 offset:17408
	ds_read_b128 v[142:145], v246 offset:18432
	ds_read_b128 v[146:149], v246 offset:19456
	ds_read_b128 v[150:153], v246 offset:20480
	ds_read_b128 v[154:157], v246 offset:21504
	ds_read_b128 v[158:161], v246 offset:22528
	ds_read_b128 v[162:165], v246 offset:23552
	global_load_lds_dwordx4 v[166:167], off
	v_lshl_add_u64 v[166:167], v[30:31], 0, s[12:13]
	s_mov_b32 m0, s29
	s_nop 0
	global_load_lds_dwordx4 v[166:167], off
	v_lshl_add_u64 v[166:167], s[14:15], 0, v[34:35]
	s_mov_b32 m0, s33
	s_nop 0
	global_load_lds_dwordx4 v[166:167], off
	v_lshl_add_u64 v[166:167], s[14:15], 0, v[32:33]
	s_mov_b32 m0, s31
	s_nop 0
	global_load_lds_dwordx4 v[166:167], off
	v_lshl_add_u64 v[166:167], v[22:23], 0, s[12:13]
	s_mov_b32 m0, s28
	s_nop 0
	global_load_lds_dwordx4 v[166:167], off
	v_lshl_add_u64 v[166:167], v[24:25], 0, s[12:13]
	s_mov_b32 m0, s27
	s_nop 0
	global_load_lds_dwordx4 v[166:167], off
	s_waitcnt vmcnt(8)
	s_waitcnt lgkmcnt(0)
	s_barrier
; #define PG8_STAGE(bufoff, gbase, voff) do { _Pragma("unroll") for (int _i = 0; _i < 2; ++_i) \
;         __builtin_amdgcn_global_load_lds((const unsigned*)((const char*)(gbase) + (voff)[_i]), (LAS unsigned*)(lds + (bufoff) + ldsw + _i * 8192), 16, 0, 0); } while (0)
; #define PG8_LDA(dst, b, h) do { _Pragma("unroll") for (int m = 0; m < 4; ++m) _Pragma("unroll") for (int k = 0; k < 2; ++k) dst[m][k] = *(const LAS bf16x8*)(lds + PG8_SA(b, h) + aoff + m * 2048 + k * 1024); } while (0)
; #define PG8_LDB(dst, b, h) do { _Pragma("unroll") for (int n = 0; n < 2; ++n) _Pragma("unroll") for (int k = 0; k < 2; ++k) dst[n][k] = *(const LAS bf16x8*)(lds + PG8_SB(b, h) + boff + n * 2048 + k * 1024); } while (0)
; #define PG8_MMA(ai, bj, At, Bt) do { __builtin_amdgcn_s_setprio(1); _Pragma("unroll") for (int m = 0; m < 4; ++m) _Pragma("unroll") for (int n = 0; n < 2; ++n) _Pragma("unroll") for (int k = 0; k < 2; ++k) \
;         acc[ai][bj][m][n] = __builtin_amdgcn_mfma_f32_16x16x32_bf16(Bt[n][k], At[m][k], acc[ai][bj][m][n], 0, 0, 0); __builtin_amdgcn_s_setprio(0); } while (0)
; #define PG8_WAIT_V(n) asm volatile("s_waitcnt vmcnt(" #n ")" ::: "memory")
; #define PG8_WAIT_L(n) asm volatile("s_waitcnt lgkmcnt(" #n ")" ::: "memory")
; #define PG8_BAR __builtin_amdgcn_s_barrier()
; #define PG8_SCHED __builtin_amdgcn_sched_barrier(0)
; template <class Epi, class Sched>
; DI void gemm_phase(LAS unsigned char* lds, const Gemm g, const Sched& S, const Epi& E) {
;     ...
;             PG8_WAIT_V(8); PG8_WAIT_L(0); PG8_BAR; PG8_MMA(0, 0, At, B0); PG8_MMA(0, 1, At, B1); PG8_BAR; PG8_SCHED;
;             PG8_LDA(At, 0, 1); PG8_STAGE(PG8_SB(0, 0), b2, voffB); PG8_STAGE(PG8_SB(0, 1), b2 + hstepB, voffB); PG8_STAGE(PG8_SA(0, 0), a2, voffA);
;             PG8_WAIT_V(8); PG8_WAIT_L(0); PG8_BAR; PG8_MMA(1, 0, At, B0); PG8_MMA(1, 1, At, B1); PG8_BAR; PG8_SCHED;
;             PG8_LDB(B0, 1, 0); PG8_LDB(B1, 1, 1); PG8_SCHED; PG8_LDA(At, 1, 0); PG8_STAGE(PG8_SA(0, 1), a2 + hstepA, voffA);
;             PG8_WAIT_V(8); PG8_WAIT_L(0); PG8_BAR; PG8_MMA(0, 0, At, B0); PG8_MMA(0, 1, At, B1); PG8_BAR; PG8_SCHED;
	s_waitcnt lgkmcnt(0)
	v_mfma_f32_16x16x32_bf16 v[166:169], v[36:39], v[96:99], 0
	v_mfma_f32_16x16x32_bf16 v[174:177], v[36:39], v[142:145], 0
	v_mfma_f32_16x16x32_bf16 v[182:185], v[36:39], v[150:153], 0
	v_mfma_f32_16x16x32_bf16 v[36:39], v[36:39], v[158:161], 0
	v_mfma_f32_16x16x32_bf16 v[166:169], v[40:43], v[138:141], v[166:169]
	v_mfma_f32_16x16x32_bf16 v[174:177], v[40:43], v[146:149], v[174:177]
	v_mfma_f32_16x16x32_bf16 v[182:185], v[40:43], v[154:157], v[182:185]
	v_mfma_f32_16x16x32_bf16 v[36:39], v[40:43], v[162:165], v[36:39]
	v_mfma_f32_16x16x32_bf16 v[40:43], v[44:47], v[158:161], 0
	v_mfma_f32_16x16x32_bf16 v[170:173], v[44:47], v[96:99], 0
	v_mfma_f32_16x16x32_bf16 v[178:181], v[44:47], v[142:145], 0
	v_mfma_f32_16x16x32_bf16 v[186:189], v[44:47], v[150:153], 0
	v_mfma_f32_16x16x32_bf16 v[40:43], v[48:51], v[162:165], v[40:43]
	v_mfma_f32_16x16x32_bf16 v[170:173], v[48:51], v[138:141], v[170:173]
	v_mfma_f32_16x16x32_bf16 v[178:181], v[48:51], v[146:149], v[178:181]
	v_mfma_f32_16x16x32_bf16 v[186:189], v[48:51], v[154:157], v[186:189]
	v_mfma_f32_16x16x32_bf16 v[44:47], v[52:55], v[96:99], 0
	v_mfma_f32_16x16x32_bf16 v[48:51], v[60:63], v[96:99], 0
	v_mfma_f32_16x16x32_bf16 v[44:47], v[56:59], v[138:141], v[44:47]
	v_mfma_f32_16x16x32_bf16 v[48:51], v[64:67], v[138:141], v[48:51]
	v_mfma_f32_16x16x32_bf16 v[96:99], v[52:55], v[142:145], 0
	v_mfma_f32_16x16x32_bf16 v[138:141], v[60:63], v[142:145], 0
	v_mfma_f32_16x16x32_bf16 v[142:145], v[52:55], v[150:153], 0
	v_mfma_f32_16x16x32_bf16 v[52:55], v[52:55], v[158:161], 0
	v_mfma_f32_16x16x32_bf16 v[96:99], v[56:59], v[146:149], v[96:99]
	v_mfma_f32_16x16x32_bf16 v[142:145], v[56:59], v[154:157], v[142:145]
	v_mfma_f32_16x16x32_bf16 v[52:55], v[56:59], v[162:165], v[52:55]
	v_mfma_f32_16x16x32_bf16 v[56:59], v[60:63], v[158:161], 0
	v_mfma_f32_16x16x32_bf16 v[138:141], v[64:67], v[146:149], v[138:141]
	v_mfma_f32_16x16x32_bf16 v[146:149], v[60:63], v[150:153], 0
	v_mfma_f32_16x16x32_bf16 v[56:59], v[64:67], v[162:165], v[56:59]
	v_mfma_f32_16x16x32_bf16 v[146:149], v[64:67], v[154:157], v[146:149]
	s_barrier
	ds_read_b128 v[60:63], v235
	ds_read_b128 v[64:67], v235 offset:1024
	ds_read_b128 v[150:153], v235 offset:2048
	ds_read_b128 v[154:157], v235 offset:3072
	ds_read_b128 v[158:161], v236
	ds_read_b128 v[162:165], v236 offset:1024
	ds_read_b128 v[190:193], v236 offset:2048
	ds_read_b128 v[194:197], v236 offset:3072
	s_mov_b32 m0, s22
	v_lshl_add_u64 v[218:219], s[10:11], 0, v[18:19]
	ds_read_b128 v[198:201], v246 offset:32768
	ds_read_b128 v[202:205], v246 offset:33792
	ds_read_b128 v[206:209], v246 offset:34816
	ds_read_b128 v[210:213], v246 offset:35840
	ds_read_b128 v[214:217], v246 offset:36864
	ds_read_b128 v[222:225], v246 offset:37888
	ds_read_b128 v[226:229], v246 offset:38912
	ds_read_b128 v[230:233], v246 offset:39936
	global_load_lds_dwordx4 v[218:219], off
	v_lshl_add_u64 v[218:219], s[10:11], 0, v[16:17]
	s_mov_b32 m0, s23
	s_nop 0
	global_load_lds_dwordx4 v[218:219], off
	s_waitcnt vmcnt(8)
	s_waitcnt lgkmcnt(0)
	s_barrier
	s_waitcnt lgkmcnt(0)
	v_mfma_f32_16x16x32_bf16 v[100:103], v[60:63], v[198:201], v[100:103]
	v_mfma_f32_16x16x32_bf16 v[104:107], v[150:153], v[198:201], v[104:107]
	v_mfma_f32_16x16x32_bf16 v[108:111], v[60:63], v[206:209], v[108:111]
	v_mfma_f32_16x16x32_bf16 v[112:115], v[150:153], v[206:209], v[112:115]
	v_mfma_f32_16x16x32_bf16 v[116:119], v[60:63], v[214:217], v[116:119]
	v_mfma_f32_16x16x32_bf16 v[120:123], v[150:153], v[214:217], v[120:123]
	v_mfma_f32_16x16x32_bf16 v[124:127], v[60:63], v[226:229], v[124:127]
	v_mfma_f32_16x16x32_bf16 v[100:103], v[64:67], v[202:205], v[100:103]
	v_mfma_f32_16x16x32_bf16 v[104:107], v[154:157], v[202:205], v[104:107]
	v_mfma_f32_16x16x32_bf16 v[108:111], v[64:67], v[210:213], v[108:111]
	v_mfma_f32_16x16x32_bf16 v[112:115], v[154:157], v[210:213], v[112:115]
	v_mfma_f32_16x16x32_bf16 v[116:119], v[64:67], v[222:225], v[116:119]
	v_mfma_f32_16x16x32_bf16 v[120:123], v[154:157], v[222:225], v[120:123]
	v_mfma_f32_16x16x32_bf16 v[124:127], v[64:67], v[230:233], v[124:127]
	v_mfma_f32_16x16x32_bf16 v[130:133], v[150:153], v[226:229], v[130:133]
	v_mfma_f32_16x16x32_bf16 v[130:133], v[154:157], v[230:233], v[130:133]
	v_mfma_f32_16x16x32_bf16 v[68:71], v[190:193], v[198:201], v[68:71]
	v_mfma_f32_16x16x32_bf16 v[72:75], v[158:161], v[206:209], v[72:75]
	v_mfma_f32_16x16x32_bf16 v[76:79], v[190:193], v[206:209], v[76:79]
	v_mfma_f32_16x16x32_bf16 v[80:83], v[158:161], v[214:217], v[80:83]
	v_mfma_f32_16x16x32_bf16 v[84:87], v[190:193], v[214:217], v[84:87]
	v_mfma_f32_16x16x32_bf16 v[88:91], v[158:161], v[226:229], v[88:91]
	v_mfma_f32_16x16x32_bf16 v[92:95], v[190:193], v[226:229], v[92:95]
	v_mfma_f32_16x16x32_bf16 v[134:137], v[158:161], v[198:201], v[134:137]
	v_mfma_f32_16x16x32_bf16 v[68:71], v[194:197], v[202:205], v[68:71]
	v_mfma_f32_16x16x32_bf16 v[72:75], v[162:165], v[210:213], v[72:75]
	v_mfma_f32_16x16x32_bf16 v[76:79], v[194:197], v[210:213], v[76:79]
	v_mfma_f32_16x16x32_bf16 v[80:83], v[162:165], v[222:225], v[80:83]
	v_mfma_f32_16x16x32_bf16 v[84:87], v[194:197], v[222:225], v[84:87]
	v_mfma_f32_16x16x32_bf16 v[88:91], v[162:165], v[230:233], v[88:91]
	v_mfma_f32_16x16x32_bf16 v[92:95], v[194:197], v[230:233], v[92:95]
	v_mfma_f32_16x16x32_bf16 v[134:137], v[162:165], v[202:205], v[134:137]
	s_barrier
; #define PG8_STAGE(bufoff, gbase, voff) do { _Pragma("unroll") for (int _i = 0; _i < 2; ++_i) \
;         __builtin_amdgcn_global_load_lds((const unsigned*)((const char*)(gbase) + (voff)[_i]), (LAS unsigned*)(lds + (bufoff) + ldsw + _i * 8192), 16, 0, 0); } while (0)
; #define PG8_LDA(dst, b, h) do { _Pragma("unroll") for (int m = 0; m < 4; ++m) _Pragma("unroll") for (int k = 0; k < 2; ++k) dst[m][k] = *(const LAS bf16x8*)(lds + PG8_SA(b, h) + aoff + m * 2048 + k * 1024); } while (0)
; #define PG8_LDB(dst, b, h) do { _Pragma("unroll") for (int n = 0; n < 2; ++n) _Pragma("unroll") for (int k = 0; k < 2; ++k) dst[n][k] = *(const LAS bf16x8*)(lds + PG8_SB(b, h) + boff + n * 2048 + k * 1024); } while (0)
; #define PG8_MMA(ai, bj, At, Bt) do { __builtin_amdgcn_s_setprio(1); _Pragma("unroll") for (int m = 0; m < 4; ++m) _Pragma("unroll") for (int n = 0; n < 2; ++n) _Pragma("unroll") for (int k = 0; k < 2; ++k) \
;         acc[ai][bj][m][n] = __builtin_amdgcn_mfma_f32_16x16x32_bf16(Bt[n][k], At[m][k], acc[ai][bj][m][n], 0, 0, 0); __builtin_amdgcn_s_setprio(0); } while (0)
; #define PG8_WAIT_V(n) asm volatile("s_waitcnt vmcnt(" #n ")" ::: "memory")
; #define PG8_WAIT_L(n) asm volatile("s_waitcnt lgkmcnt(" #n ")" ::: "memory")
; template <class Epi, class Sched>
; DI void gemm_phase(LAS unsigned char* lds, const Gemm g, const Sched& S, const Epi& E) {
;     ...
;             PG8_LDB(B0, 0, 0); PG8_LDB(B1, 0, 1); PG8_SCHED; PG8_LDA(At, 0, 0); PG8_STAGE(PG8_SA(1, 1), a1 + hstepA, voffA);
;             PG8_WAIT_V(8); PG8_WAIT_L(0); PG8_BAR; PG8_MMA(0, 0, At, B0); PG8_MMA(0, 1, At, B1); PG8_BAR; PG8_SCHED;
;             PG8_LDA(At, 0, 1); PG8_STAGE(PG8_SB(0, 0), b2, voffB); PG8_STAGE(PG8_SB(0, 1), b2 + hstepB, voffB); PG8_STAGE(PG8_SA(0, 0), a2, voffA);
;             PG8_WAIT_V(8); PG8_WAIT_L(0); PG8_BAR; PG8_MMA(1, 0, At, B0); PG8_MMA(1, 1, At, B1); PG8_BAR; PG8_SCHED;
;             PG8_LDB(B0, 1, 0); PG8_LDB(B1, 1, 1); PG8_SCHED; PG8_LDA(At, 1, 0); PG8_STAGE(PG8_SA(0, 1), a2 + hstepA, voffA);
;             PG8_WAIT_V(8); PG8_WAIT_L(0); PG8_BAR; PG8_MMA(0, 0, At, B0); PG8_MMA(0, 1, At, B1); PG8_BAR; PG8_SCHED;
;             PG8_LDA(At, 1, 1); PG8_STAGE(PG8_SB(1, 0), b3, voffB); PG8_STAGE(PG8_SB(1, 1), b3 + hstepB, voffB); PG8_STAGE(PG8_SA(1, 0), a3, voffA);
;             PG8_WAIT_V(8); PG8_WAIT_L(0); PG8_BAR; PG8_MMA(1, 0, At, B0); PG8_MMA(1, 1, At, B1); PG8_BAR; PG8_SCHED;
	s_mov_b64 s[10:11], 0x180
	s_mov_b32 m0, s3
	v_lshl_add_u64 v[218:219], v[28:29], 0, s[10:11]
	ds_read_b128 v[198:201], v246 offset:49152
	ds_read_b128 v[202:205], v246 offset:50176
	ds_read_b128 v[206:209], v246 offset:51200
	ds_read_b128 v[210:213], v246 offset:52224
	ds_read_b128 v[214:217], v246 offset:53248
	ds_read_b128 v[222:225], v246 offset:54272
	ds_read_b128 v[226:229], v246 offset:55296
	ds_read_b128 v[230:233], v246 offset:56320
	global_load_lds_dwordx4 v[218:219], off
	v_lshl_add_u64 v[218:219], v[30:31], 0, s[10:11]
	s_mov_b32 m0, s20
	v_lshl_add_u64 v[34:35], s[8:9], 0, v[34:35]
	global_load_lds_dwordx4 v[218:219], off
	s_mov_b32 m0, s24
	v_lshl_add_u64 v[32:33], s[8:9], 0, v[32:33]
	global_load_lds_dwordx4 v[34:35], off
	s_mov_b32 m0, s25
	s_nop 0
	global_load_lds_dwordx4 v[32:33], off
	v_lshl_add_u64 v[32:33], v[22:23], 0, s[10:11]
	s_mov_b32 m0, s5
	s_nop 0
	global_load_lds_dwordx4 v[32:33], off
	v_lshl_add_u64 v[32:33], v[24:25], 0, s[10:11]
	s_mov_b32 m0, s21
	s_nop 0
	global_load_lds_dwordx4 v[32:33], off
	s_waitcnt vmcnt(8)
	s_waitcnt lgkmcnt(0)
	s_barrier
	s_waitcnt lgkmcnt(0)
	v_mfma_f32_16x16x32_bf16 v[32:35], v[60:63], v[198:201], v[166:169]
	v_mfma_f32_16x16x32_bf16 v[36:39], v[60:63], v[226:229], v[36:39]
	v_mfma_f32_16x16x32_bf16 v[40:43], v[150:153], v[226:229], v[40:43]
	v_mfma_f32_16x16x32_bf16 v[32:35], v[64:67], v[202:205], v[32:35]
	v_mfma_f32_16x16x32_bf16 v[166:169], v[150:153], v[198:201], v[170:173]
	v_mfma_f32_16x16x32_bf16 v[170:173], v[60:63], v[206:209], v[174:177]
	v_mfma_f32_16x16x32_bf16 v[174:177], v[150:153], v[206:209], v[178:181]
	v_mfma_f32_16x16x32_bf16 v[178:181], v[60:63], v[214:217], v[182:185]
	v_mfma_f32_16x16x32_bf16 v[182:185], v[150:153], v[214:217], v[186:189]
	v_mfma_f32_16x16x32_bf16 v[36:39], v[64:67], v[230:233], v[36:39]
	v_mfma_f32_16x16x32_bf16 v[40:43], v[154:157], v[230:233], v[40:43]
	v_mfma_f32_16x16x32_bf16 v[166:169], v[154:157], v[202:205], v[166:169]
	v_mfma_f32_16x16x32_bf16 v[170:173], v[64:67], v[210:213], v[170:173]
	v_mfma_f32_16x16x32_bf16 v[174:177], v[154:157], v[210:213], v[174:177]
	v_mfma_f32_16x16x32_bf16 v[178:181], v[64:67], v[222:225], v[178:181]
	v_mfma_f32_16x16x32_bf16 v[182:185], v[154:157], v[222:225], v[182:185]
	v_mfma_f32_16x16x32_bf16 v[44:47], v[158:161], v[198:201], v[44:47]
	v_mfma_f32_16x16x32_bf16 v[48:51], v[190:193], v[198:201], v[48:51]
	v_mfma_f32_16x16x32_bf16 v[60:63], v[158:161], v[206:209], v[96:99]
	v_mfma_f32_16x16x32_bf16 v[64:67], v[190:193], v[206:209], v[138:141]
	v_mfma_f32_16x16x32_bf16 v[96:99], v[158:161], v[214:217], v[142:145]
	v_mfma_f32_16x16x32_bf16 v[52:55], v[158:161], v[226:229], v[52:55]
	v_mfma_f32_16x16x32_bf16 v[56:59], v[190:193], v[226:229], v[56:59]
	v_mfma_f32_16x16x32_bf16 v[44:47], v[162:165], v[202:205], v[44:47]
	v_mfma_f32_16x16x32_bf16 v[48:51], v[194:197], v[202:205], v[48:51]
	v_mfma_f32_16x16x32_bf16 v[60:63], v[162:165], v[210:213], v[60:63]
	v_mfma_f32_16x16x32_bf16 v[64:67], v[194:197], v[210:213], v[64:67]
	v_mfma_f32_16x16x32_bf16 v[96:99], v[162:165], v[222:225], v[96:99]
	v_mfma_f32_16x16x32_bf16 v[138:141], v[190:193], v[214:217], v[146:149]
	v_mfma_f32_16x16x32_bf16 v[52:55], v[162:165], v[230:233], v[52:55]
	v_mfma_f32_16x16x32_bf16 v[56:59], v[194:197], v[230:233], v[56:59]
	v_mfma_f32_16x16x32_bf16 v[138:141], v[194:197], v[222:225], v[138:141]
	s_barrier
	ds_read_b128 v[142:145], v221
	ds_read_b128 v[146:149], v221 offset:1024
	ds_read_b128 v[150:153], v221 offset:2048
	ds_read_b128 v[154:157], v221 offset:3072
	ds_read_b128 v[158:161], v234
	ds_read_b128 v[162:165], v234 offset:1024
	ds_read_b128 v[186:189], v234 offset:2048
	ds_read_b128 v[190:193], v234 offset:3072
	s_mov_b32 m0, s35
	v_lshl_add_u64 v[18:19], s[6:7], 0, v[18:19]
	ds_read_b128 v[194:197], v246
	ds_read_b128 v[198:201], v246 offset:1024
	ds_read_b128 v[202:205], v246 offset:2048
	ds_read_b128 v[206:209], v246 offset:3072
	ds_read_b128 v[210:213], v246 offset:4096
	ds_read_b128 v[214:217], v246 offset:5120
	ds_read_b128 v[222:225], v246 offset:6144
	ds_read_b128 v[226:229], v246 offset:7168
	global_load_lds_dwordx4 v[18:19], off
	v_lshl_add_u64 v[16:17], s[6:7], 0, v[16:17]
	s_mov_b32 m0, s34
	s_nop 0
	global_load_lds_dwordx4 v[16:17], off
	s_waitcnt vmcnt(8)
	s_waitcnt lgkmcnt(0)
	s_barrier
	s_waitcnt lgkmcnt(0)
	v_mfma_f32_16x16x32_bf16 v[16:19], v[142:145], v[194:197], v[100:103]
	v_mfma_f32_16x16x32_bf16 v[100:103], v[150:153], v[194:197], v[104:107]
	v_mfma_f32_16x16x32_bf16 v[104:107], v[142:145], v[202:205], v[108:111]
	v_mfma_f32_16x16x32_bf16 v[108:111], v[150:153], v[202:205], v[112:115]
	v_mfma_f32_16x16x32_bf16 v[112:115], v[142:145], v[210:213], v[116:119]
	v_mfma_f32_16x16x32_bf16 v[230:233], v[146:149], v[214:217], v[112:115]
	v_mfma_f32_16x16x32_bf16 v[112:115], v[150:153], v[210:213], v[120:123]
	v_mfma_f32_16x16x32_bf16 v[120:123], v[154:157], v[214:217], v[112:115]
	v_mfma_f32_16x16x32_bf16 v[112:115], v[142:145], v[222:225], v[124:127]
	v_mfma_f32_16x16x32_bf16 v[16:19], v[146:149], v[198:201], v[16:19]
	v_mfma_f32_16x16x32_bf16 v[100:103], v[154:157], v[198:201], v[100:103]
	v_mfma_f32_16x16x32_bf16 v[104:107], v[146:149], v[206:209], v[104:107]
	v_mfma_f32_16x16x32_bf16 v[108:111], v[154:157], v[206:209], v[108:111]
	v_mfma_f32_16x16x32_bf16 v[124:127], v[146:149], v[226:229], v[112:115]
	v_mfma_f32_16x16x32_bf16 v[112:115], v[150:153], v[222:225], v[130:133]
	v_mfma_f32_16x16x32_bf16 v[130:133], v[154:157], v[226:229], v[112:115]
	v_mfma_f32_16x16x32_bf16 v[68:71], v[186:189], v[194:197], v[68:71]
	v_mfma_f32_16x16x32_bf16 v[112:115], v[158:161], v[194:197], v[134:137]
	v_mfma_f32_16x16x32_bf16 v[194:197], v[190:193], v[198:201], v[68:71]
	v_mfma_f32_16x16x32_bf16 v[68:71], v[158:161], v[202:205], v[72:75]
	v_mfma_f32_16x16x32_bf16 v[134:137], v[162:165], v[198:201], v[112:115]
	v_mfma_f32_16x16x32_bf16 v[198:201], v[162:165], v[206:209], v[68:71]
	v_mfma_f32_16x16x32_bf16 v[68:71], v[186:189], v[202:205], v[76:79]
	v_mfma_f32_16x16x32_bf16 v[76:79], v[190:193], v[206:209], v[68:71]
	v_mfma_f32_16x16x32_bf16 v[68:71], v[158:161], v[210:213], v[80:83]
	v_mfma_f32_16x16x32_bf16 v[80:83], v[162:165], v[214:217], v[68:71]
	v_mfma_f32_16x16x32_bf16 v[68:71], v[186:189], v[210:213], v[84:87]
	v_mfma_f32_16x16x32_bf16 v[84:87], v[190:193], v[214:217], v[68:71]
	v_mfma_f32_16x16x32_bf16 v[68:71], v[158:161], v[222:225], v[88:91]
	v_mfma_f32_16x16x32_bf16 v[202:205], v[162:165], v[226:229], v[68:71]
	v_mfma_f32_16x16x32_bf16 v[68:71], v[186:189], v[222:225], v[92:95]
	v_mfma_f32_16x16x32_bf16 v[92:95], v[190:193], v[226:229], v[68:71]
	s_barrier
; #define PG8_STAGE(bufoff, gbase, voff) do { _Pragma("unroll") for (int _i = 0; _i < 2; ++_i) \
;         __builtin_amdgcn_global_load_lds((const unsigned*)((const char*)(gbase) + (voff)[_i]), (LAS unsigned*)(lds + (bufoff) + ldsw + _i * 8192), 16, 0, 0); } while (0)
; #define PG8_LDA(dst, b, h) do { _Pragma("unroll") for (int m = 0; m < 4; ++m) _Pragma("unroll") for (int k = 0; k < 2; ++k) dst[m][k] = *(const LAS bf16x8*)(lds + PG8_SA(b, h) + aoff + m * 2048 + k * 1024); } while (0)
; #define PG8_LDB(dst, b, h) do { _Pragma("unroll") for (int n = 0; n < 2; ++n) _Pragma("unroll") for (int k = 0; k < 2; ++k) dst[n][k] = *(const LAS bf16x8*)(lds + PG8_SB(b, h) + boff + n * 2048 + k * 1024); } while (0)
; #define PG8_MMA(ai, bj, At, Bt) do { __builtin_amdgcn_s_setprio(1); _Pragma("unroll") for (int m = 0; m < 4; ++m) _Pragma("unroll") for (int n = 0; n < 2; ++n) _Pragma("unroll") for (int k = 0; k < 2; ++k) \
;         acc[ai][bj][m][n] = __builtin_amdgcn_mfma_f32_16x16x32_bf16(Bt[n][k], At[m][k], acc[ai][bj][m][n], 0, 0, 0); __builtin_amdgcn_s_setprio(0); } while (0)
; #define PG8_WAIT_V(n) asm volatile("s_waitcnt vmcnt(" #n ")" ::: "memory")
; #define PG8_WAIT_L(n) asm volatile("s_waitcnt lgkmcnt(" #n ")" ::: "memory")
; #define PG8_BAR __builtin_amdgcn_s_barrier()
; #define PG8_SCHED __builtin_amdgcn_sched_barrier(0)
; template <class Epi, class Sched>
; DI void gemm_phase(LAS unsigned char* lds, const Gemm g, const Sched& S, const Epi& E) {
;     ...
;             PG8_LDA(At, 0, 1); PG8_STAGE(PG8_SB(0, 0), b2, voffB); PG8_STAGE(PG8_SB(0, 1), b2 + hstepB, voffB); PG8_STAGE(PG8_SA(0, 0), a2, voffA);
;             PG8_WAIT_V(8); PG8_WAIT_L(0); PG8_BAR; PG8_MMA(1, 0, At, B0); PG8_MMA(1, 1, At, B1); PG8_BAR; PG8_SCHED;
;             PG8_LDB(B0, 1, 0); PG8_LDB(B1, 1, 1); PG8_SCHED; PG8_LDA(At, 1, 0); PG8_STAGE(PG8_SA(0, 1), a2 + hstepA, voffA);
;             PG8_WAIT_V(8); PG8_WAIT_L(0); PG8_BAR; PG8_MMA(0, 0, At, B0); PG8_MMA(0, 1, At, B1); PG8_BAR; PG8_SCHED;
	s_mov_b32 m0, s30
	s_nop 3
	ds_read_b128 v[68:71], v246 offset:16384
	ds_read_b128 v[72:75], v246 offset:17408
	ds_read_b128 v[88:91], v246 offset:18432
	ds_read_b128 v[112:115], v246 offset:19456
	ds_read_b128 v[116:119], v246 offset:20480
	ds_read_b128 v[206:209], v246 offset:21504
	ds_read_b128 v[210:213], v246 offset:22528
	ds_read_b128 v[214:217], v246 offset:23552
	global_load_lds_dwordx4 v[28:29], off
	s_mov_b32 m0, s29
	s_nop 0
	global_load_lds_dwordx4 v[30:31], off
	s_mov_b32 m0, s33
	s_nop 0
	global_load_lds_dwordx4 v[26:27], off
	s_mov_b32 m0, s31
	s_nop 0
	global_load_lds_dwordx4 v[20:21], off
	s_mov_b32 m0, s28
	s_nop 0
	global_load_lds_dwordx4 v[22:23], off
	s_mov_b32 m0, s27
	s_nop 0
	global_load_lds_dwordx4 v[24:25], off
	s_waitcnt vmcnt(8)
	s_waitcnt lgkmcnt(0)
	s_barrier
	s_waitcnt lgkmcnt(0)
	v_mfma_f32_16x16x32_bf16 v[20:23], v[142:145], v[68:71], v[32:35]
	v_mfma_f32_16x16x32_bf16 v[24:27], v[150:153], v[68:71], v[166:169]
	v_mfma_f32_16x16x32_bf16 v[28:31], v[142:145], v[88:91], v[170:173]
	v_mfma_f32_16x16x32_bf16 v[32:35], v[150:153], v[88:91], v[174:177]
	v_mfma_f32_16x16x32_bf16 v[36:39], v[142:145], v[210:213], v[36:39]
	v_mfma_f32_16x16x32_bf16 v[20:23], v[146:149], v[72:75], v[20:23]
	v_mfma_f32_16x16x32_bf16 v[24:27], v[154:157], v[72:75], v[24:27]
	v_mfma_f32_16x16x32_bf16 v[28:31], v[146:149], v[112:115], v[28:31]
	v_mfma_f32_16x16x32_bf16 v[32:35], v[154:157], v[112:115], v[32:35]
	v_mfma_f32_16x16x32_bf16 v[166:169], v[142:145], v[116:119], v[178:181]
	v_mfma_f32_16x16x32_bf16 v[170:173], v[150:153], v[116:119], v[182:185]
	v_mfma_f32_16x16x32_bf16 v[142:145], v[146:149], v[214:217], v[36:39]
	v_mfma_f32_16x16x32_bf16 v[36:39], v[150:153], v[210:213], v[40:43]
	v_mfma_f32_16x16x32_bf16 v[166:169], v[146:149], v[206:209], v[166:169]
	v_mfma_f32_16x16x32_bf16 v[170:173], v[154:157], v[206:209], v[170:173]
	v_mfma_f32_16x16x32_bf16 v[146:149], v[154:157], v[214:217], v[36:39]
	v_mfma_f32_16x16x32_bf16 v[36:39], v[158:161], v[68:71], v[44:47]
	v_mfma_f32_16x16x32_bf16 v[150:153], v[162:165], v[72:75], v[36:39]
	v_mfma_f32_16x16x32_bf16 v[36:39], v[186:189], v[68:71], v[48:51]
	v_mfma_f32_16x16x32_bf16 v[154:157], v[190:193], v[72:75], v[36:39]
	v_mfma_f32_16x16x32_bf16 v[36:39], v[158:161], v[88:91], v[60:63]
	v_mfma_f32_16x16x32_bf16 v[60:63], v[162:165], v[112:115], v[36:39]
	v_mfma_f32_16x16x32_bf16 v[36:39], v[186:189], v[88:91], v[64:67]
	v_mfma_f32_16x16x32_bf16 v[174:177], v[190:193], v[112:115], v[36:39]
	v_mfma_f32_16x16x32_bf16 v[36:39], v[158:161], v[116:119], v[96:99]
	v_mfma_f32_16x16x32_bf16 v[178:181], v[162:165], v[206:209], v[36:39]
	v_mfma_f32_16x16x32_bf16 v[36:39], v[186:189], v[116:119], v[138:141]
	v_mfma_f32_16x16x32_bf16 v[138:141], v[190:193], v[206:209], v[36:39]
	v_mfma_f32_16x16x32_bf16 v[36:39], v[158:161], v[210:213], v[52:55]
	v_mfma_f32_16x16x32_bf16 v[158:161], v[162:165], v[214:217], v[36:39]
	v_mfma_f32_16x16x32_bf16 v[36:39], v[186:189], v[210:213], v[56:59]
	v_mfma_f32_16x16x32_bf16 v[162:165], v[190:193], v[214:217], v[36:39]
	s_barrier
	ds_read_b128 v[52:55], v235
	ds_read_b128 v[182:185], v235 offset:1024
	ds_read_b128 v[186:189], v235 offset:2048
	ds_read_b128 v[190:193], v235 offset:3072
	ds_read_b128 v[206:209], v236
	ds_read_b128 v[210:213], v236 offset:1024
	ds_read_b128 v[214:217], v236 offset:2048
	ds_read_b128 v[222:225], v236 offset:3072
	s_mov_b32 m0, s22
	ds_read_b128 v[44:47], v246 offset:32768
	ds_read_b128 v[48:51], v246 offset:33792
	ds_read_b128 v[56:59], v246 offset:34816
	ds_read_b128 v[64:67], v246 offset:35840
	ds_read_b128 v[226:229], v246 offset:36864
	ds_read_b128 v[234:237], v246 offset:37888
	ds_read_b128 v[238:241], v246 offset:38912
	ds_read_b128 v[242:245], v246 offset:39936
	global_load_lds_dwordx4 v[12:13], off
	s_mov_b32 m0, s23
	s_nop 0
	global_load_lds_dwordx4 v[14:15], off
	s_waitcnt vmcnt(8)
	s_waitcnt lgkmcnt(0)
	s_barrier
; #define PG8_STAGE(bufoff, gbase, voff) do { _Pragma("unroll") for (int _i = 0; _i < 2; ++_i) \
;         __builtin_amdgcn_global_load_lds((const unsigned*)((const char*)(gbase) + (voff)[_i]), (LAS unsigned*)(lds + (bufoff) + ldsw + _i * 8192), 16, 0, 0); } while (0)
; #define PG8_LDA(dst, b, h) do { _Pragma("unroll") for (int m = 0; m < 4; ++m) _Pragma("unroll") for (int k = 0; k < 2; ++k) dst[m][k] = *(const LAS bf16x8*)(lds + PG8_SA(b, h) + aoff + m * 2048 + k * 1024); } while (0)
; #define PG8_LDB(dst, b, h) do { _Pragma("unroll") for (int n = 0; n < 2; ++n) _Pragma("unroll") for (int k = 0; k < 2; ++k) dst[n][k] = *(const LAS bf16x8*)(lds + PG8_SB(b, h) + boff + n * 2048 + k * 1024); } while (0)
; #define PG8_MMA(ai, bj, At, Bt) do { __builtin_amdgcn_s_setprio(1); _Pragma("unroll") for (int m = 0; m < 4; ++m) _Pragma("unroll") for (int n = 0; n < 2; ++n) _Pragma("unroll") for (int k = 0; k < 2; ++k) \
;         acc[ai][bj][m][n] = __builtin_amdgcn_mfma_f32_16x16x32_bf16(Bt[n][k], At[m][k], acc[ai][bj][m][n], 0, 0, 0); __builtin_amdgcn_s_setprio(0); } while (0)
; #define PG8_WAIT_V(n) asm volatile("s_waitcnt vmcnt(" #n ")" ::: "memory")
; #define PG8_WAIT_L(n) asm volatile("s_waitcnt lgkmcnt(" #n ")" ::: "memory")
; #define PG8_BAR __builtin_amdgcn_s_barrier()
; #define PG8_SCHED __builtin_amdgcn_sched_barrier(0)
; template <class Epi, class Sched>
; DI void gemm_phase(LAS unsigned char* lds, const Gemm g, const Sched& S, const Epi& E) {
;     ...
;             PG8_LDB(B0, 1, 0); PG8_LDB(B1, 1, 1); PG8_SCHED; PG8_LDA(At, 1, 0); PG8_STAGE(PG8_SA(0, 1), a2 + hstepA, voffA);
;             PG8_WAIT_V(8); PG8_WAIT_L(0); PG8_BAR; PG8_MMA(0, 0, At, B0); PG8_MMA(0, 1, At, B1); PG8_BAR; PG8_SCHED;
;             PG8_LDA(At, 1, 1); PG8_STAGE(PG8_SB(1, 0), b3, voffB); PG8_STAGE(PG8_SB(1, 1), b3 + hstepB, voffB); PG8_STAGE(PG8_SA(1, 0), a3, voffA);
;             PG8_WAIT_V(8); PG8_WAIT_L(0); PG8_BAR; PG8_MMA(1, 0, At, B0); PG8_MMA(1, 1, At, B1); PG8_BAR; PG8_SCHED;
;         }
;         if (wr == 0) PG8_BAR;
	s_waitcnt lgkmcnt(0)
	v_mfma_f32_16x16x32_bf16 v[12:15], v[52:55], v[44:47], v[16:19]
	v_mfma_f32_16x16x32_bf16 v[116:119], v[182:185], v[48:51], v[12:15]
	v_mfma_f32_16x16x32_bf16 v[12:15], v[186:189], v[44:47], v[100:103]
	v_mfma_f32_16x16x32_bf16 v[112:115], v[190:193], v[48:51], v[12:15]
	v_mfma_f32_16x16x32_bf16 v[12:15], v[52:55], v[56:59], v[104:107]
	v_mfma_f32_16x16x32_bf16 v[100:103], v[182:185], v[64:67], v[12:15]
	v_mfma_f32_16x16x32_bf16 v[12:15], v[186:189], v[56:59], v[108:111]
	v_mfma_f32_16x16x32_bf16 v[96:99], v[190:193], v[64:67], v[12:15]
	v_mfma_f32_16x16x32_bf16 v[12:15], v[52:55], v[226:229], v[230:233]
	v_mfma_f32_16x16x32_bf16 v[72:75], v[182:185], v[234:237], v[12:15]
	v_mfma_f32_16x16x32_bf16 v[12:15], v[186:189], v[226:229], v[120:123]
	v_mfma_f32_16x16x32_bf16 v[68:71], v[190:193], v[234:237], v[12:15]
	v_mfma_f32_16x16x32_bf16 v[12:15], v[52:55], v[238:241], v[124:127]
	v_mfma_f32_16x16x32_bf16 v[40:43], v[182:185], v[242:245], v[12:15]
	v_mfma_f32_16x16x32_bf16 v[12:15], v[186:189], v[238:241], v[130:133]
	v_mfma_f32_16x16x32_bf16 v[36:39], v[190:193], v[242:245], v[12:15]
	v_mfma_f32_16x16x32_bf16 v[12:15], v[206:209], v[44:47], v[134:137]
	v_mfma_f32_16x16x32_bf16 v[124:127], v[210:213], v[48:51], v[12:15]
	v_mfma_f32_16x16x32_bf16 v[12:15], v[214:217], v[44:47], v[194:197]
	v_mfma_f32_16x16x32_bf16 v[120:123], v[222:225], v[48:51], v[12:15]
	v_mfma_f32_16x16x32_bf16 v[12:15], v[206:209], v[56:59], v[198:201]
	v_mfma_f32_16x16x32_bf16 v[108:111], v[210:213], v[64:67], v[12:15]
	v_mfma_f32_16x16x32_bf16 v[12:15], v[214:217], v[56:59], v[76:79]
	v_mfma_f32_16x16x32_bf16 v[104:107], v[222:225], v[64:67], v[12:15]
	v_mfma_f32_16x16x32_bf16 v[12:15], v[206:209], v[226:229], v[80:83]
	v_mfma_f32_16x16x32_bf16 v[88:91], v[210:213], v[234:237], v[12:15]
	v_mfma_f32_16x16x32_bf16 v[12:15], v[214:217], v[226:229], v[84:87]
	v_mfma_f32_16x16x32_bf16 v[80:83], v[222:225], v[234:237], v[12:15]
	v_mfma_f32_16x16x32_bf16 v[12:15], v[206:209], v[238:241], v[202:205]
	v_mfma_f32_16x16x32_bf16 v[56:59], v[210:213], v[242:245], v[12:15]
	v_mfma_f32_16x16x32_bf16 v[12:15], v[214:217], v[238:241], v[92:95]
	v_mfma_f32_16x16x32_bf16 v[48:51], v[222:225], v[242:245], v[12:15]
	s_barrier
	s_mov_b32 m0, s3
	s_nop 3
	ds_read_b128 v[12:15], v246 offset:49152
	ds_read_b128 v[84:87], v246 offset:50176
	ds_read_b128 v[130:133], v246 offset:51200
	ds_read_b128 v[134:137], v246 offset:52224
	ds_read_b128 v[194:197], v246 offset:53248
	ds_read_b128 v[198:201], v246 offset:54272
	ds_read_b128 v[202:205], v246 offset:55296
	ds_read_b128 v[226:229], v246 offset:56320
	global_load_lds_dwordx4 v[2:3], off
	s_mov_b32 m0, s20
	s_nop 0
	global_load_lds_dwordx4 v[4:5], off
	s_mov_b32 m0, s24
	s_nop 0
	global_load_lds_dwordx4 v[8:9], off
	s_mov_b32 m0, s25
	s_nop 0
	global_load_lds_dwordx4 v[10:11], off
	s_mov_b32 m0, s5
	s_nop 0
	global_load_lds_dwordx4 v[0:1], off
	s_mov_b32 m0, s21
	s_nop 0
	global_load_lds_dwordx4 v[6:7], off
	s_waitcnt vmcnt(8)
	s_waitcnt lgkmcnt(0)
	s_barrier
	s_waitcnt lgkmcnt(0)
	v_mfma_f32_16x16x32_bf16 v[0:3], v[52:55], v[12:15], v[20:23]
	v_mfma_f32_16x16x32_bf16 v[76:79], v[182:185], v[84:87], v[0:3]
	v_mfma_f32_16x16x32_bf16 v[0:3], v[186:189], v[12:15], v[24:27]
	v_mfma_f32_16x16x32_bf16 v[64:67], v[190:193], v[84:87], v[0:3]
	v_mfma_f32_16x16x32_bf16 v[0:3], v[52:55], v[130:133], v[28:31]
	v_mfma_f32_16x16x32_bf16 v[44:47], v[182:185], v[134:137], v[0:3]
	v_mfma_f32_16x16x32_bf16 v[0:3], v[186:189], v[130:133], v[32:35]
	v_mfma_f32_16x16x32_bf16 v[32:35], v[190:193], v[134:137], v[0:3]
	v_mfma_f32_16x16x32_bf16 v[0:3], v[52:55], v[194:197], v[166:169]
	v_mfma_f32_16x16x32_bf16 v[20:23], v[182:185], v[198:201], v[0:3]
	v_mfma_f32_16x16x32_bf16 v[0:3], v[186:189], v[194:197], v[170:173]
	v_mfma_f32_16x16x32_bf16 v[16:19], v[190:193], v[198:201], v[0:3]
	v_mfma_f32_16x16x32_bf16 v[0:3], v[52:55], v[202:205], v[142:145]
	v_mfma_f32_16x16x32_bf16 v[4:7], v[182:185], v[226:229], v[0:3]
	v_mfma_f32_16x16x32_bf16 v[0:3], v[186:189], v[202:205], v[146:149]
	v_mfma_f32_16x16x32_bf16 v[0:3], v[190:193], v[226:229], v[0:3]
	v_mfma_f32_16x16x32_bf16 v[8:11], v[206:209], v[12:15], v[150:153]
	v_mfma_f32_16x16x32_bf16 v[12:15], v[214:217], v[12:15], v[154:157]
	v_mfma_f32_16x16x32_bf16 v[92:95], v[210:213], v[84:87], v[8:11]
	v_mfma_f32_16x16x32_bf16 v[8:11], v[206:209], v[130:133], v[60:63]
	v_mfma_f32_16x16x32_bf16 v[84:87], v[222:225], v[84:87], v[12:15]
	v_mfma_f32_16x16x32_bf16 v[12:15], v[214:217], v[130:133], v[174:177]
	v_mfma_f32_16x16x32_bf16 v[60:63], v[210:213], v[134:137], v[8:11]
	v_mfma_f32_16x16x32_bf16 v[8:11], v[206:209], v[194:197], v[178:181]
	v_mfma_f32_16x16x32_bf16 v[52:55], v[222:225], v[134:137], v[12:15]
	v_mfma_f32_16x16x32_bf16 v[12:15], v[214:217], v[194:197], v[138:141]
	v_mfma_f32_16x16x32_bf16 v[28:31], v[210:213], v[198:201], v[8:11]
	v_mfma_f32_16x16x32_bf16 v[8:11], v[206:209], v[202:205], v[158:161]
	v_mfma_f32_16x16x32_bf16 v[24:27], v[222:225], v[198:201], v[12:15]
	v_mfma_f32_16x16x32_bf16 v[12:15], v[210:213], v[226:229], v[8:11]
	v_mfma_f32_16x16x32_bf16 v[8:11], v[214:217], v[202:205], v[162:165]
	v_mfma_f32_16x16x32_bf16 v[8:11], v[222:225], v[226:229], v[8:11]
	s_barrier
	s_cbranch_scc1 .LBB0_122
	s_barrier

; #define PG8_STAGE(bufoff, gbase, voff) do { _Pragma("unroll") for (int _i = 0; _i < 2; ++_i) \
;         __builtin_amdgcn_global_load_lds((const unsigned*)((const char*)(gbase) + (voff)[_i]), (LAS unsigned*)(lds + (bufoff) + ldsw + _i * 8192), 16, 0, 0); } while (0)
; #define PG8_LDA(dst, b, h) do { _Pragma("unroll") for (int m = 0; m < 4; ++m) _Pragma("unroll") for (int k = 0; k < 2; ++k) dst[m][k] = *(const LAS bf16x8*)(lds + PG8_SA(b, h) + aoff + m * 2048 + k * 1024); } while (0)
; #define PG8_LDB(dst, b, h) do { _Pragma("unroll") for (int n = 0; n < 2; ++n) _Pragma("unroll") for (int k = 0; k < 2; ++k) dst[n][k] = *(const LAS bf16x8*)(lds + PG8_SB(b, h) + boff + n * 2048 + k * 1024); } while (0)
; #define PG8_MMA(ai, bj, At, Bt) do { __builtin_amdgcn_s_setprio(1); _Pragma("unroll") for (int m = 0; m < 4; ++m) _Pragma("unroll") for (int n = 0; n < 2; ++n) _Pragma("unroll") for (int k = 0; k < 2; ++k) \
;         acc[ai][bj][m][n] = __builtin_amdgcn_mfma_f32_16x16x32_bf16(Bt[n][k], At[m][k], acc[ai][bj][m][n], 0, 0, 0); __builtin_amdgcn_s_setprio(0); } while (0)
; #define PG8_WAIT_V(n) asm volatile("s_waitcnt vmcnt(" #n ")" ::: "memory")
; #define PG8_WAIT_L(n) asm volatile("s_waitcnt lgkmcnt(" #n ")" ::: "memory")
; #define PG8_BAR __builtin_amdgcn_s_barrier()
; #define PG8_SCHED __builtin_amdgcn_sched_barrier(0)
; template <class Epi, class Sched>
; DI void gemm_phase(LAS unsigned char* lds, const Gemm g, const Sched& S, const Epi& E) {
;     ...
;             const bool last = (t == nt - 2);
;             const char* a1 = cA + (size_t)(t + 1) * kstep;
;             const char* a2 = last ? nA : cA + (size_t)(t + 2) * kstep; const char* b2 = last ? nB : cB + (size_t)(t + 2) * kstep;
;             const char* a3 = a2 + kstep; const char* b3 = b2 + kstep;
;             PG8_LDB(B0, 0, 0); PG8_LDB(B1, 0, 1); PG8_SCHED; PG8_LDA(At, 0, 0); PG8_STAGE(PG8_SA(1, 1), a1 + hstepA, voffA);
;             PG8_WAIT_V(8); PG8_WAIT_L(0); PG8_BAR; PG8_MMA(0, 0, At, B0); PG8_MMA(0, 1, At, B1); PG8_BAR; PG8_SCHED;
;             PG8_LDA(At, 0, 1); PG8_STAGE(PG8_SB(0, 0), b2, voffB); PG8_STAGE(PG8_SB(0, 1), b2 + hstepB, voffB); PG8_STAGE(PG8_SA(0, 0), a2, voffA);
;             PG8_WAIT_V(8); PG8_WAIT_L(0); PG8_BAR; PG8_MMA(1, 0, At, B0); PG8_MMA(1, 1, At, B1); PG8_BAR; PG8_SCHED;
.LBB0_210:
	s_add_u32 s9, s38, 0xfff80080
	s_addc_u32 s10, s39, -1
	s_add_i32 s11, 0, 0x10000
	s_cmp_eq_u32 s8, 28
	s_cselect_b32 s75, s59, s10
	s_cselect_b32 s74, vcc_lo, s9
	s_cselect_b32 s73, s31, s7
	s_cselect_b32 s72, vcc_hi, s6
	s_add_i32 s9, 0, 0x14000
	v_add_u32_e32 v108, s11, v154
	v_add_u32_e32 v159, s9, v154
	ds_read_b128 v[96:99], v108
	ds_read_b128 v[100:103], v108 offset:1024
	ds_read_b128 v[104:107], v108 offset:2048
	ds_read_b128 v[108:111], v108 offset:3072
	ds_read_b128 v[160:163], v159
	ds_read_b128 v[164:167], v159 offset:1024
	ds_read_b128 v[168:171], v159 offset:2048
	ds_read_b128 v[172:175], v159 offset:3072
	v_lshl_add_u64 v[208:209], s[38:39], 0, v[148:149]
	s_add_i32 m0, s69, 0xc000
	ds_read_b128 v[176:179], v157
	ds_read_b128 v[180:183], v157 offset:1024
	ds_read_b128 v[184:187], v157 offset:2048
	ds_read_b128 v[188:191], v157 offset:3072
	ds_read_b128 v[192:195], v157 offset:4096
	ds_read_b128 v[196:199], v157 offset:5120
	ds_read_b128 v[200:203], v157 offset:6144
	ds_read_b128 v[204:207], v157 offset:7168
	global_load_lds_dwordx4 v[208:209], off
	v_lshl_add_u64 v[208:209], s[38:39], 0, v[150:151]
	s_add_i32 m0, s69, 0xe000
	s_nop 0
	global_load_lds_dwordx4 v[208:209], off
	s_waitcnt vmcnt(8)
	s_waitcnt lgkmcnt(0)
	s_barrier
	s_waitcnt lgkmcnt(0)
	v_mfma_f32_16x16x32_bf16 v[140:143], v[96:99], v[176:179], v[140:143]
	v_mfma_f32_16x16x32_bf16 v[136:139], v[104:107], v[176:179], v[136:139]
	v_mfma_f32_16x16x32_bf16 v[124:127], v[96:99], v[184:187], v[124:127]
	v_mfma_f32_16x16x32_bf16 v[120:123], v[104:107], v[184:187], v[120:123]
	v_mfma_f32_16x16x32_bf16 v[92:95], v[96:99], v[192:195], v[92:95]
	v_mfma_f32_16x16x32_bf16 v[88:91], v[104:107], v[192:195], v[88:91]
	v_mfma_f32_16x16x32_bf16 v[76:79], v[96:99], v[200:203], v[76:79]
	v_mfma_f32_16x16x32_bf16 v[72:75], v[104:107], v[200:203], v[72:75]
	v_mfma_f32_16x16x32_bf16 v[140:143], v[100:103], v[180:183], v[140:143]
	v_mfma_f32_16x16x32_bf16 v[136:139], v[108:111], v[180:183], v[136:139]
	v_mfma_f32_16x16x32_bf16 v[124:127], v[100:103], v[188:191], v[124:127]
	v_mfma_f32_16x16x32_bf16 v[120:123], v[108:111], v[188:191], v[120:123]
	v_mfma_f32_16x16x32_bf16 v[92:95], v[100:103], v[196:199], v[92:95]
	v_mfma_f32_16x16x32_bf16 v[88:91], v[108:111], v[196:199], v[88:91]
	v_mfma_f32_16x16x32_bf16 v[76:79], v[100:103], v[204:207], v[76:79]
	v_mfma_f32_16x16x32_bf16 v[72:75], v[108:111], v[204:207], v[72:75]
	v_mfma_f32_16x16x32_bf16 v[132:135], v[160:163], v[176:179], v[132:135]
	v_mfma_f32_16x16x32_bf16 v[128:131], v[168:171], v[176:179], v[128:131]
	v_mfma_f32_16x16x32_bf16 v[116:119], v[160:163], v[184:187], v[116:119]
	v_mfma_f32_16x16x32_bf16 v[112:115], v[168:171], v[184:187], v[112:115]
	v_mfma_f32_16x16x32_bf16 v[84:87], v[160:163], v[192:195], v[84:87]
	v_mfma_f32_16x16x32_bf16 v[80:83], v[168:171], v[192:195], v[80:83]
	v_mfma_f32_16x16x32_bf16 v[68:71], v[160:163], v[200:203], v[68:71]
	v_mfma_f32_16x16x32_bf16 v[64:67], v[168:171], v[200:203], v[64:67]
	v_mfma_f32_16x16x32_bf16 v[132:135], v[164:167], v[180:183], v[132:135]
	v_mfma_f32_16x16x32_bf16 v[128:131], v[172:175], v[180:183], v[128:131]
	v_mfma_f32_16x16x32_bf16 v[116:119], v[164:167], v[188:191], v[116:119]
	v_mfma_f32_16x16x32_bf16 v[112:115], v[172:175], v[188:191], v[112:115]
	v_mfma_f32_16x16x32_bf16 v[84:87], v[164:167], v[196:199], v[84:87]
	v_mfma_f32_16x16x32_bf16 v[80:83], v[172:175], v[196:199], v[80:83]
	v_mfma_f32_16x16x32_bf16 v[68:71], v[164:167], v[204:207], v[68:71]
	v_mfma_f32_16x16x32_bf16 v[64:67], v[172:175], v[204:207], v[64:67]
	s_barrier
	s_add_i32 s10, s11, s96
	v_lshl_add_u64 v[208:209], s[72:73], 0, v[144:145]
	s_mov_b32 m0, s10
	ds_read_b128 v[176:179], v157 offset:16384
	ds_read_b128 v[180:183], v157 offset:17408
	ds_read_b128 v[184:187], v157 offset:18432
	ds_read_b128 v[188:191], v157 offset:19456
	ds_read_b128 v[192:195], v157 offset:20480
	ds_read_b128 v[196:199], v157 offset:21504
	ds_read_b128 v[200:203], v157 offset:22528
	ds_read_b128 v[204:207], v157 offset:23552
	global_load_lds_dwordx4 v[208:209], off
	s_add_i32 m0, s10, 0x2000
	s_add_u32 s10, s72, 0x80000
	v_lshl_add_u64 v[210:211], s[72:73], 0, v[146:147]
	s_addc_u32 s11, s73, 0
	s_add_i32 s9, s9, s96
	global_load_lds_dwordx4 v[210:211], off
	v_lshl_add_u64 v[212:213], s[10:11], 0, v[144:145]
	s_mov_b32 m0, s9
	v_lshl_add_u64 v[214:215], s[74:75], 0, v[146:147]
	global_load_lds_dwordx4 v[212:213], off
	v_lshl_add_u64 v[212:213], s[10:11], 0, v[146:147]
	s_add_i32 m0, s9, 0x2000
	s_nop 0
	global_load_lds_dwordx4 v[212:213], off
	v_lshl_add_u64 v[212:213], s[74:75], 0, v[144:145]
	s_mov_b32 m0, s69
	s_nop 0
	global_load_lds_dwordx4 v[212:213], off
	s_mov_b32 m0, s71
	s_nop 0
	global_load_lds_dwordx4 v[214:215], off
	s_waitcnt vmcnt(8)
	s_waitcnt lgkmcnt(0)
	s_barrier
; #define PG8_STAGE(bufoff, gbase, voff) do { _Pragma("unroll") for (int _i = 0; _i < 2; ++_i) \
;         __builtin_amdgcn_global_load_lds((const unsigned*)((const char*)(gbase) + (voff)[_i]), (LAS unsigned*)(lds + (bufoff) + ldsw + _i * 8192), 16, 0, 0); } while (0)
; #define PG8_LDA(dst, b, h) do { _Pragma("unroll") for (int m = 0; m < 4; ++m) _Pragma("unroll") for (int k = 0; k < 2; ++k) dst[m][k] = *(const LAS bf16x8*)(lds + PG8_SA(b, h) + aoff + m * 2048 + k * 1024); } while (0)
; #define PG8_LDB(dst, b, h) do { _Pragma("unroll") for (int n = 0; n < 2; ++n) _Pragma("unroll") for (int k = 0; k < 2; ++k) dst[n][k] = *(const LAS bf16x8*)(lds + PG8_SB(b, h) + boff + n * 2048 + k * 1024); } while (0)
; #define PG8_MMA(ai, bj, At, Bt) do { __builtin_amdgcn_s_setprio(1); _Pragma("unroll") for (int m = 0; m < 4; ++m) _Pragma("unroll") for (int n = 0; n < 2; ++n) _Pragma("unroll") for (int k = 0; k < 2; ++k) \
;         acc[ai][bj][m][n] = __builtin_amdgcn_mfma_f32_16x16x32_bf16(Bt[n][k], At[m][k], acc[ai][bj][m][n], 0, 0, 0); __builtin_amdgcn_s_setprio(0); } while (0)
; #define PG8_WAIT_V(n) asm volatile("s_waitcnt vmcnt(" #n ")" ::: "memory")
; #define PG8_WAIT_L(n) asm volatile("s_waitcnt lgkmcnt(" #n ")" ::: "memory")
; #define PG8_BAR __builtin_amdgcn_s_barrier()
; #define PG8_SCHED __builtin_amdgcn_sched_barrier(0)
; template <class Epi, class Sched>
; DI void gemm_phase(LAS unsigned char* lds, const Gemm g, const Sched& S, const Epi& E) {
;     ...
;             PG8_LDA(At, 0, 1); PG8_STAGE(PG8_SB(0, 0), b2, voffB); PG8_STAGE(PG8_SB(0, 1), b2 + hstepB, voffB); PG8_STAGE(PG8_SA(0, 0), a2, voffA);
;             PG8_WAIT_V(8); PG8_WAIT_L(0); PG8_BAR; PG8_MMA(1, 0, At, B0); PG8_MMA(1, 1, At, B1); PG8_BAR; PG8_SCHED;
;             PG8_LDB(B0, 1, 0); PG8_LDB(B1, 1, 1); PG8_SCHED; PG8_LDA(At, 1, 0); PG8_STAGE(PG8_SA(0, 1), a2 + hstepA, voffA);
;             PG8_WAIT_V(8); PG8_WAIT_L(0); PG8_BAR; PG8_MMA(0, 0, At, B0); PG8_MMA(0, 1, At, B1); PG8_BAR; PG8_SCHED;
	s_waitcnt lgkmcnt(0)
	v_mfma_f32_16x16x32_bf16 v[60:63], v[96:99], v[176:179], v[60:63]
	v_mfma_f32_16x16x32_bf16 v[56:59], v[104:107], v[176:179], v[56:59]
	v_mfma_f32_16x16x32_bf16 v[44:47], v[96:99], v[184:187], v[44:47]
	v_mfma_f32_16x16x32_bf16 v[40:43], v[104:107], v[184:187], v[40:43]
	v_mfma_f32_16x16x32_bf16 v[28:31], v[96:99], v[192:195], v[28:31]
	v_mfma_f32_16x16x32_bf16 v[24:27], v[104:107], v[192:195], v[24:27]
	v_mfma_f32_16x16x32_bf16 v[12:15], v[96:99], v[200:203], v[12:15]
	v_mfma_f32_16x16x32_bf16 v[8:11], v[104:107], v[200:203], v[8:11]
	v_mfma_f32_16x16x32_bf16 v[60:63], v[100:103], v[180:183], v[60:63]
	v_mfma_f32_16x16x32_bf16 v[56:59], v[108:111], v[180:183], v[56:59]
	v_mfma_f32_16x16x32_bf16 v[44:47], v[100:103], v[188:191], v[44:47]
	v_mfma_f32_16x16x32_bf16 v[40:43], v[108:111], v[188:191], v[40:43]
	v_mfma_f32_16x16x32_bf16 v[28:31], v[100:103], v[196:199], v[28:31]
	v_mfma_f32_16x16x32_bf16 v[24:27], v[108:111], v[196:199], v[24:27]
	v_mfma_f32_16x16x32_bf16 v[12:15], v[100:103], v[204:207], v[12:15]
	v_mfma_f32_16x16x32_bf16 v[8:11], v[108:111], v[204:207], v[8:11]
	v_mfma_f32_16x16x32_bf16 v[52:55], v[160:163], v[176:179], v[52:55]
	v_mfma_f32_16x16x32_bf16 v[48:51], v[168:171], v[176:179], v[48:51]
	v_mfma_f32_16x16x32_bf16 v[36:39], v[160:163], v[184:187], v[36:39]
	v_mfma_f32_16x16x32_bf16 v[32:35], v[168:171], v[184:187], v[32:35]
	v_mfma_f32_16x16x32_bf16 v[20:23], v[160:163], v[192:195], v[20:23]
	v_mfma_f32_16x16x32_bf16 v[16:19], v[168:171], v[192:195], v[16:19]
	v_mfma_f32_16x16x32_bf16 v[4:7], v[160:163], v[200:203], v[4:7]
	v_mfma_f32_16x16x32_bf16 v[0:3], v[168:171], v[200:203], v[0:3]
	v_mfma_f32_16x16x32_bf16 v[52:55], v[164:167], v[180:183], v[52:55]
	v_mfma_f32_16x16x32_bf16 v[48:51], v[172:175], v[180:183], v[48:51]
	v_mfma_f32_16x16x32_bf16 v[36:39], v[164:167], v[188:191], v[36:39]
	v_mfma_f32_16x16x32_bf16 v[32:35], v[172:175], v[188:191], v[32:35]
	v_mfma_f32_16x16x32_bf16 v[20:23], v[164:167], v[196:199], v[20:23]
	v_mfma_f32_16x16x32_bf16 v[16:19], v[172:175], v[196:199], v[16:19]
	v_mfma_f32_16x16x32_bf16 v[4:7], v[164:167], v[204:207], v[4:7]
	v_mfma_f32_16x16x32_bf16 v[0:3], v[172:175], v[204:207], v[0:3]
	s_barrier
	s_add_i32 s9, 0, 0x18000
	s_add_i32 s12, 0, 0x1c000
	v_add_u32_e32 v108, s9, v154
	v_add_u32_e32 v159, s12, v154
	ds_read_b128 v[96:99], v108
	ds_read_b128 v[100:103], v108 offset:1024
	ds_read_b128 v[104:107], v108 offset:2048
	ds_read_b128 v[108:111], v108 offset:3072
	ds_read_b128 v[160:163], v159
	ds_read_b128 v[164:167], v159 offset:1024
	ds_read_b128 v[168:171], v159 offset:2048
	ds_read_b128 v[172:175], v159 offset:3072
	s_add_u32 s10, s74, 0x80000
	s_addc_u32 s11, s75, 0
	s_mov_b32 m0, s97
	v_lshl_add_u64 v[216:217], s[10:11], 0, v[144:145]
	ds_read_b128 v[176:179], v157 offset:32768
	ds_read_b128 v[180:183], v157 offset:33792
	ds_read_b128 v[184:187], v157 offset:34816
	ds_read_b128 v[188:191], v157 offset:35840
	ds_read_b128 v[192:195], v157 offset:36864
	ds_read_b128 v[196:199], v157 offset:37888
	ds_read_b128 v[200:203], v157 offset:38912
	ds_read_b128 v[204:207], v157 offset:39936
	global_load_lds_dwordx4 v[216:217], off
	v_lshl_add_u64 v[216:217], s[10:11], 0, v[146:147]
	s_mov_b32 m0, s98
	s_nop 0
	global_load_lds_dwordx4 v[216:217], off
	s_waitcnt vmcnt(8)
	s_waitcnt lgkmcnt(0)
	s_barrier
	s_waitcnt lgkmcnt(0)
	v_mfma_f32_16x16x32_bf16 v[140:143], v[96:99], v[176:179], v[140:143]
	v_mfma_f32_16x16x32_bf16 v[136:139], v[104:107], v[176:179], v[136:139]
	v_mfma_f32_16x16x32_bf16 v[124:127], v[96:99], v[184:187], v[124:127]
	v_mfma_f32_16x16x32_bf16 v[120:123], v[104:107], v[184:187], v[120:123]
	v_mfma_f32_16x16x32_bf16 v[92:95], v[96:99], v[192:195], v[92:95]
	v_mfma_f32_16x16x32_bf16 v[88:91], v[104:107], v[192:195], v[88:91]
	v_mfma_f32_16x16x32_bf16 v[76:79], v[96:99], v[200:203], v[76:79]
	v_mfma_f32_16x16x32_bf16 v[72:75], v[104:107], v[200:203], v[72:75]
	v_mfma_f32_16x16x32_bf16 v[140:143], v[100:103], v[180:183], v[140:143]
	v_mfma_f32_16x16x32_bf16 v[136:139], v[108:111], v[180:183], v[136:139]
	v_mfma_f32_16x16x32_bf16 v[124:127], v[100:103], v[188:191], v[124:127]
	v_mfma_f32_16x16x32_bf16 v[120:123], v[108:111], v[188:191], v[120:123]
	v_mfma_f32_16x16x32_bf16 v[92:95], v[100:103], v[196:199], v[92:95]
	v_mfma_f32_16x16x32_bf16 v[88:91], v[108:111], v[196:199], v[88:91]
	v_mfma_f32_16x16x32_bf16 v[76:79], v[100:103], v[204:207], v[76:79]
	v_mfma_f32_16x16x32_bf16 v[72:75], v[108:111], v[204:207], v[72:75]
	v_mfma_f32_16x16x32_bf16 v[132:135], v[160:163], v[176:179], v[132:135]
	v_mfma_f32_16x16x32_bf16 v[128:131], v[168:171], v[176:179], v[128:131]
	v_mfma_f32_16x16x32_bf16 v[116:119], v[160:163], v[184:187], v[116:119]
	v_mfma_f32_16x16x32_bf16 v[112:115], v[168:171], v[184:187], v[112:115]
	v_mfma_f32_16x16x32_bf16 v[84:87], v[160:163], v[192:195], v[84:87]
	v_mfma_f32_16x16x32_bf16 v[80:83], v[168:171], v[192:195], v[80:83]
	v_mfma_f32_16x16x32_bf16 v[68:71], v[160:163], v[200:203], v[68:71]
	v_mfma_f32_16x16x32_bf16 v[64:67], v[168:171], v[200:203], v[64:67]
	v_mfma_f32_16x16x32_bf16 v[132:135], v[164:167], v[180:183], v[132:135]
	v_mfma_f32_16x16x32_bf16 v[128:131], v[172:175], v[180:183], v[128:131]
	v_mfma_f32_16x16x32_bf16 v[116:119], v[164:167], v[188:191], v[116:119]
	v_mfma_f32_16x16x32_bf16 v[112:115], v[172:175], v[188:191], v[112:115]
	v_mfma_f32_16x16x32_bf16 v[84:87], v[164:167], v[196:199], v[84:87]
	v_mfma_f32_16x16x32_bf16 v[80:83], v[172:175], v[196:199], v[80:83]
	v_mfma_f32_16x16x32_bf16 v[68:71], v[164:167], v[204:207], v[68:71]
	v_mfma_f32_16x16x32_bf16 v[64:67], v[172:175], v[204:207], v[64:67]
	s_barrier
; #define PG8_STAGE(bufoff, gbase, voff) do { _Pragma("unroll") for (int _i = 0; _i < 2; ++_i) \
;         __builtin_amdgcn_global_load_lds((const unsigned*)((const char*)(gbase) + (voff)[_i]), (LAS unsigned*)(lds + (bufoff) + ldsw + _i * 8192), 16, 0, 0); } while (0)
; #define PG8_LDA(dst, b, h) do { _Pragma("unroll") for (int m = 0; m < 4; ++m) _Pragma("unroll") for (int k = 0; k < 2; ++k) dst[m][k] = *(const LAS bf16x8*)(lds + PG8_SA(b, h) + aoff + m * 2048 + k * 1024); } while (0)
; #define PG8_MMA(ai, bj, At, Bt) do { __builtin_amdgcn_s_setprio(1); _Pragma("unroll") for (int m = 0; m < 4; ++m) _Pragma("unroll") for (int n = 0; n < 2; ++n) _Pragma("unroll") for (int k = 0; k < 2; ++k) \
;         acc[ai][bj][m][n] = __builtin_amdgcn_mfma_f32_16x16x32_bf16(Bt[n][k], At[m][k], acc[ai][bj][m][n], 0, 0, 0); __builtin_amdgcn_s_setprio(0); } while (0)
; #define PG8_WAIT_V(n) asm volatile("s_waitcnt vmcnt(" #n ")" ::: "memory")
; #define PG8_WAIT_L(n) asm volatile("s_waitcnt lgkmcnt(" #n ")" ::: "memory")
; #define PG8_BAR __builtin_amdgcn_s_barrier()
; #define PG8_SCHED __builtin_amdgcn_sched_barrier(0)
; template <class Epi, class Sched>
; DI void gemm_phase(LAS unsigned char* lds, const Gemm g, const Sched& S, const Epi& E) {
;     ...
;             PG8_LDA(At, 1, 1); PG8_STAGE(PG8_SB(1, 0), b3, voffB); PG8_STAGE(PG8_SB(1, 1), b3 + hstepB, voffB); PG8_STAGE(PG8_SA(1, 0), a3, voffA);
;             PG8_WAIT_V(8); PG8_WAIT_L(0); PG8_BAR; PG8_MMA(1, 0, At, B0); PG8_MMA(1, 1, At, B1); PG8_BAR; PG8_SCHED;
;         }
;         if (wr == 0) PG8_BAR;
	s_add_i32 s9, s9, s96
	v_lshl_add_u64 v[208:209], v[208:209], 0, s[28:29]
	s_mov_b32 m0, s9
	ds_read_b128 v[176:179], v157 offset:49152
	ds_read_b128 v[180:183], v157 offset:50176
	ds_read_b128 v[184:187], v157 offset:51200
	ds_read_b128 v[188:191], v157 offset:52224
	ds_read_b128 v[192:195], v157 offset:53248
	ds_read_b128 v[196:199], v157 offset:54272
	ds_read_b128 v[200:203], v157 offset:55296
	ds_read_b128 v[204:207], v157 offset:56320
	global_load_lds_dwordx4 v[208:209], off
	s_add_i32 m0, s9, 0x2000
	s_add_u32 s10, s72, 0x80080
	v_lshl_add_u64 v[208:209], v[210:211], 0, s[28:29]
	s_addc_u32 s11, s73, 0
	s_add_i32 s9, s12, s96
	global_load_lds_dwordx4 v[208:209], off
	v_lshl_add_u64 v[208:209], s[10:11], 0, v[144:145]
	s_mov_b32 m0, s9
	s_nop 0
	global_load_lds_dwordx4 v[208:209], off
	v_lshl_add_u64 v[208:209], s[10:11], 0, v[146:147]
	s_add_i32 m0, s9, 0x2000
	s_nop 0
	global_load_lds_dwordx4 v[208:209], off
	v_lshl_add_u64 v[208:209], v[212:213], 0, s[28:29]
	s_mov_b32 m0, s0
	s_nop 0
	global_load_lds_dwordx4 v[208:209], off
	v_lshl_add_u64 v[208:209], v[214:215], 0, s[28:29]
	s_mov_b32 m0, s1
	s_nop 0
	global_load_lds_dwordx4 v[208:209], off
	s_waitcnt vmcnt(8)
	s_waitcnt lgkmcnt(0)
	s_barrier
	s_waitcnt lgkmcnt(0)
	v_mfma_f32_16x16x32_bf16 v[60:63], v[96:99], v[176:179], v[60:63]
	v_mfma_f32_16x16x32_bf16 v[56:59], v[104:107], v[176:179], v[56:59]
	v_mfma_f32_16x16x32_bf16 v[44:47], v[96:99], v[184:187], v[44:47]
	v_mfma_f32_16x16x32_bf16 v[40:43], v[104:107], v[184:187], v[40:43]
	v_mfma_f32_16x16x32_bf16 v[28:31], v[96:99], v[192:195], v[28:31]
	v_mfma_f32_16x16x32_bf16 v[24:27], v[104:107], v[192:195], v[24:27]
	v_mfma_f32_16x16x32_bf16 v[12:15], v[96:99], v[200:203], v[12:15]
	v_mfma_f32_16x16x32_bf16 v[8:11], v[104:107], v[200:203], v[8:11]
	v_mfma_f32_16x16x32_bf16 v[60:63], v[100:103], v[180:183], v[60:63]
	v_mfma_f32_16x16x32_bf16 v[56:59], v[108:111], v[180:183], v[56:59]
	v_mfma_f32_16x16x32_bf16 v[44:47], v[100:103], v[188:191], v[44:47]
	v_mfma_f32_16x16x32_bf16 v[40:43], v[108:111], v[188:191], v[40:43]
	v_mfma_f32_16x16x32_bf16 v[28:31], v[100:103], v[196:199], v[28:31]
	v_mfma_f32_16x16x32_bf16 v[24:27], v[108:111], v[196:199], v[24:27]
	v_mfma_f32_16x16x32_bf16 v[12:15], v[100:103], v[204:207], v[12:15]
	v_mfma_f32_16x16x32_bf16 v[8:11], v[108:111], v[204:207], v[8:11]
	v_mfma_f32_16x16x32_bf16 v[52:55], v[160:163], v[176:179], v[52:55]
	v_mfma_f32_16x16x32_bf16 v[48:51], v[168:171], v[176:179], v[48:51]
	v_mfma_f32_16x16x32_bf16 v[36:39], v[160:163], v[184:187], v[36:39]
	v_mfma_f32_16x16x32_bf16 v[32:35], v[168:171], v[184:187], v[32:35]
	v_mfma_f32_16x16x32_bf16 v[20:23], v[160:163], v[192:195], v[20:23]
	v_mfma_f32_16x16x32_bf16 v[16:19], v[168:171], v[192:195], v[16:19]
	v_mfma_f32_16x16x32_bf16 v[4:7], v[160:163], v[200:203], v[4:7]
	v_mfma_f32_16x16x32_bf16 v[0:3], v[168:171], v[200:203], v[0:3]
	v_mfma_f32_16x16x32_bf16 v[52:55], v[164:167], v[180:183], v[52:55]
	v_mfma_f32_16x16x32_bf16 v[48:51], v[172:175], v[180:183], v[48:51]
	v_mfma_f32_16x16x32_bf16 v[36:39], v[164:167], v[188:191], v[36:39]
	v_mfma_f32_16x16x32_bf16 v[32:35], v[172:175], v[188:191], v[32:35]
	v_mfma_f32_16x16x32_bf16 v[20:23], v[164:167], v[196:199], v[20:23]
	v_mfma_f32_16x16x32_bf16 v[16:19], v[172:175], v[196:199], v[16:19]
	v_mfma_f32_16x16x32_bf16 v[4:7], v[164:167], v[204:207], v[4:7]
	v_mfma_f32_16x16x32_bf16 v[0:3], v[172:175], v[204:207], v[0:3]
	s_barrier
	s_add_i32 s8, s8, 2
	s_add_u32 s38, s38, 0x100
	s_addc_u32 s39, s39, 0
	s_add_u32 s6, s6, 0x100
	s_addc_u32 s7, s7, 0
	s_cmp_gt_u32 s8, 29
	s_cbranch_scc0 .LBB0_210
	s_and_b64 vcc, exec, s[60:61]
	s_cbranch_vccz .LBB0_213
	s_barrier

; #define PG8_STAGE(bufoff, gbase, voff) do { _Pragma("unroll") for (int _i = 0; _i < 2; ++_i) \
;         __builtin_amdgcn_global_load_lds((const unsigned*)((const char*)(gbase) + (voff)[_i]), (LAS unsigned*)(lds + (bufoff) + ldsw + _i * 8192), 16, 0, 0); } while (0)
; #define PG8_LDA(dst, b, h) do { _Pragma("unroll") for (int m = 0; m < 4; ++m) _Pragma("unroll") for (int k = 0; k < 2; ++k) dst[m][k] = *(const LAS bf16x8*)(lds + PG8_SA(b, h) + aoff + m * 2048 + k * 1024); } while (0)
; #define PG8_LDB(dst, b, h) do { _Pragma("unroll") for (int n = 0; n < 2; ++n) _Pragma("unroll") for (int k = 0; k < 2; ++k) dst[n][k] = *(const LAS bf16x8*)(lds + PG8_SB(b, h) + boff + n * 2048 + k * 1024); } while (0)
; #define PG8_MMA(ai, bj, At, Bt) do { __builtin_amdgcn_s_setprio(1); _Pragma("unroll") for (int m = 0; m < 4; ++m) _Pragma("unroll") for (int n = 0; n < 2; ++n) _Pragma("unroll") for (int k = 0; k < 2; ++k) \
;         acc[ai][bj][m][n] = __builtin_amdgcn_mfma_f32_16x16x32_bf16(Bt[n][k], At[m][k], acc[ai][bj][m][n], 0, 0, 0); __builtin_amdgcn_s_setprio(0); } while (0)
; #define PG8_WAIT_V(n) asm volatile("s_waitcnt vmcnt(" #n ")" ::: "memory")
; #define PG8_WAIT_L(n) asm volatile("s_waitcnt lgkmcnt(" #n ")" ::: "memory")
; #define PG8_BAR __builtin_amdgcn_s_barrier()
; #define PG8_SCHED __builtin_amdgcn_sched_barrier(0)
; template <class Epi, class Sched>
; DI void gemm_phase(LAS unsigned char* lds, const Gemm g, const Sched& S, const Epi& E) {
;     ...
;         for (int t = 0; t < nt; t += 2) {
;             const bool last = (t == nt - 2);
;             const char* a1 = cA + (size_t)(t + 1) * kstep;
;             const char* a2 = last ? nA : cA + (size_t)(t + 2) * kstep; const char* b2 = last ? nB : cB + (size_t)(t + 2) * kstep;
;             const char* a3 = a2 + kstep; const char* b3 = b2 + kstep;
;             PG8_LDB(B0, 0, 0); PG8_LDB(B1, 0, 1); PG8_SCHED; PG8_LDA(At, 0, 0); PG8_STAGE(PG8_SA(1, 1), a1 + hstepA, voffA);
;             PG8_WAIT_V(8); PG8_WAIT_L(0); PG8_BAR; PG8_MMA(0, 0, At, B0); PG8_MMA(0, 1, At, B1); PG8_BAR; PG8_SCHED;
;             PG8_LDA(At, 0, 1); PG8_STAGE(PG8_SB(0, 0), b2, voffB); PG8_STAGE(PG8_SB(0, 1), b2 + hstepB, voffB); PG8_STAGE(PG8_SA(0, 0), a2, voffA);
;             PG8_WAIT_V(8); PG8_WAIT_L(0); PG8_BAR; PG8_MMA(1, 0, At, B0); PG8_MMA(1, 1, At, B1); PG8_BAR; PG8_SCHED;
.LBB0_417:
	s_add_u32 s9, s66, 0xfff80080
	s_addc_u32 s10, s67, -1
	s_add_i32 s11, 0, 0x10000
	s_cmp_eq_u32 s8, 28
	s_cselect_b32 s71, s31, s10
	s_cselect_b32 s70, s37, s9
	s_cselect_b32 s69, s39, s7
	s_cselect_b32 s68, s59, s6
	s_add_i32 s9, 0, 0x14000
	v_add_u32_e32 v72, s11, v167
	v_add_u32_e32 v162, s9, v167
	ds_read_b128 v[56:59], v72
	ds_read_b128 v[60:63], v72 offset:1024
	ds_read_b128 v[68:71], v72 offset:2048
	ds_read_b128 v[72:75], v72 offset:3072
	ds_read_b128 v[144:147], v162
	ds_read_b128 v[148:151], v162 offset:1024
	ds_read_b128 v[158:161], v162 offset:2048
	ds_read_b128 v[162:165], v162 offset:3072
	v_lshl_add_u64 v[202:203], s[66:67], 0, v[154:155]
	s_add_i32 m0, s5, 0xc000
	ds_read_b128 v[170:173], v169
	ds_read_b128 v[174:177], v169 offset:1024
	ds_read_b128 v[178:181], v169 offset:2048
	ds_read_b128 v[182:185], v169 offset:3072
	ds_read_b128 v[186:189], v169 offset:4096
	ds_read_b128 v[190:193], v169 offset:5120
	ds_read_b128 v[194:197], v169 offset:6144
	ds_read_b128 v[198:201], v169 offset:7168
	global_load_lds_dwordx4 v[202:203], off
	v_lshl_add_u64 v[202:203], s[66:67], 0, v[156:157]
	s_add_i32 m0, s5, 0xe000
	s_nop 0
	global_load_lds_dwordx4 v[202:203], off
	s_waitcnt vmcnt(8)
	s_waitcnt lgkmcnt(0)
	s_barrier
	s_waitcnt lgkmcnt(0)
	v_mfma_f32_16x16x32_bf16 v[140:143], v[56:59], v[170:173], v[140:143]
	v_mfma_f32_16x16x32_bf16 v[136:139], v[68:71], v[170:173], v[136:139]
	v_mfma_f32_16x16x32_bf16 v[124:127], v[56:59], v[178:181], v[124:127]
	v_mfma_f32_16x16x32_bf16 v[120:123], v[68:71], v[178:181], v[120:123]
	v_mfma_f32_16x16x32_bf16 v[108:111], v[56:59], v[186:189], v[108:111]
	v_mfma_f32_16x16x32_bf16 v[104:107], v[68:71], v[186:189], v[104:107]
	v_mfma_f32_16x16x32_bf16 v[92:95], v[56:59], v[194:197], v[92:95]
	v_mfma_f32_16x16x32_bf16 v[88:91], v[68:71], v[194:197], v[88:91]
	v_mfma_f32_16x16x32_bf16 v[140:143], v[60:63], v[174:177], v[140:143]
	v_mfma_f32_16x16x32_bf16 v[136:139], v[72:75], v[174:177], v[136:139]
	v_mfma_f32_16x16x32_bf16 v[124:127], v[60:63], v[182:185], v[124:127]
	v_mfma_f32_16x16x32_bf16 v[120:123], v[72:75], v[182:185], v[120:123]
	v_mfma_f32_16x16x32_bf16 v[108:111], v[60:63], v[190:193], v[108:111]
	v_mfma_f32_16x16x32_bf16 v[104:107], v[72:75], v[190:193], v[104:107]
	v_mfma_f32_16x16x32_bf16 v[92:95], v[60:63], v[198:201], v[92:95]
	v_mfma_f32_16x16x32_bf16 v[88:91], v[72:75], v[198:201], v[88:91]
	v_mfma_f32_16x16x32_bf16 v[132:135], v[144:147], v[170:173], v[132:135]
	v_mfma_f32_16x16x32_bf16 v[128:131], v[158:161], v[170:173], v[128:131]
	v_mfma_f32_16x16x32_bf16 v[116:119], v[144:147], v[178:181], v[116:119]
	v_mfma_f32_16x16x32_bf16 v[112:115], v[158:161], v[178:181], v[112:115]
	v_mfma_f32_16x16x32_bf16 v[100:103], v[144:147], v[186:189], v[100:103]
	v_mfma_f32_16x16x32_bf16 v[96:99], v[158:161], v[186:189], v[96:99]
	v_mfma_f32_16x16x32_bf16 v[84:87], v[144:147], v[194:197], v[84:87]
	v_mfma_f32_16x16x32_bf16 v[80:83], v[158:161], v[194:197], v[80:83]
	v_mfma_f32_16x16x32_bf16 v[132:135], v[148:151], v[174:177], v[132:135]
	v_mfma_f32_16x16x32_bf16 v[128:131], v[162:165], v[174:177], v[128:131]
	v_mfma_f32_16x16x32_bf16 v[116:119], v[148:151], v[182:185], v[116:119]
	v_mfma_f32_16x16x32_bf16 v[112:115], v[162:165], v[182:185], v[112:115]
	v_mfma_f32_16x16x32_bf16 v[100:103], v[148:151], v[190:193], v[100:103]
	v_mfma_f32_16x16x32_bf16 v[96:99], v[162:165], v[190:193], v[96:99]
	v_mfma_f32_16x16x32_bf16 v[84:87], v[148:151], v[198:201], v[84:87]
	v_mfma_f32_16x16x32_bf16 v[80:83], v[162:165], v[198:201], v[80:83]
	s_barrier
	s_add_i32 s10, s11, s4
	v_lshl_add_u64 v[202:203], s[68:69], 0, v[222:223]
	s_mov_b32 m0, s10
	ds_read_b128 v[170:173], v169 offset:16384
	ds_read_b128 v[174:177], v169 offset:17408
	ds_read_b128 v[178:181], v169 offset:18432
	ds_read_b128 v[182:185], v169 offset:19456
	ds_read_b128 v[186:189], v169 offset:20480
	ds_read_b128 v[190:193], v169 offset:21504
	ds_read_b128 v[194:197], v169 offset:22528
	ds_read_b128 v[198:201], v169 offset:23552
	global_load_lds_dwordx4 v[202:203], off
	s_add_i32 m0, s10, 0x2000
	s_add_u32 s10, s68, 0x80000
	v_lshl_add_u64 v[204:205], s[68:69], 0, v[152:153]
	s_addc_u32 s11, s69, 0
	s_add_i32 s9, s9, s4
	global_load_lds_dwordx4 v[204:205], off
	v_lshl_add_u64 v[206:207], s[10:11], 0, v[222:223]
	s_mov_b32 m0, s9
	v_lshl_add_u64 v[208:209], s[70:71], 0, v[152:153]
	global_load_lds_dwordx4 v[206:207], off
	v_lshl_add_u64 v[206:207], s[10:11], 0, v[152:153]
	s_add_i32 m0, s9, 0x2000
	s_nop 0
	global_load_lds_dwordx4 v[206:207], off
	v_lshl_add_u64 v[206:207], s[70:71], 0, v[222:223]
	s_mov_b32 m0, s5
	s_nop 0
	global_load_lds_dwordx4 v[206:207], off
	s_mov_b32 m0, s72
	s_nop 0
	global_load_lds_dwordx4 v[208:209], off
	s_waitcnt vmcnt(8)
	s_waitcnt lgkmcnt(0)
	s_barrier
; #define PG8_STAGE(bufoff, gbase, voff) do { _Pragma("unroll") for (int _i = 0; _i < 2; ++_i) \
;         __builtin_amdgcn_global_load_lds((const unsigned*)((const char*)(gbase) + (voff)[_i]), (LAS unsigned*)(lds + (bufoff) + ldsw + _i * 8192), 16, 0, 0); } while (0)
; #define PG8_LDA(dst, b, h) do { _Pragma("unroll") for (int m = 0; m < 4; ++m) _Pragma("unroll") for (int k = 0; k < 2; ++k) dst[m][k] = *(const LAS bf16x8*)(lds + PG8_SA(b, h) + aoff + m * 2048 + k * 1024); } while (0)
; #define PG8_LDB(dst, b, h) do { _Pragma("unroll") for (int n = 0; n < 2; ++n) _Pragma("unroll") for (int k = 0; k < 2; ++k) dst[n][k] = *(const LAS bf16x8*)(lds + PG8_SB(b, h) + boff + n * 2048 + k * 1024); } while (0)
; #define PG8_MMA(ai, bj, At, Bt) do { __builtin_amdgcn_s_setprio(1); _Pragma("unroll") for (int m = 0; m < 4; ++m) _Pragma("unroll") for (int n = 0; n < 2; ++n) _Pragma("unroll") for (int k = 0; k < 2; ++k) \
;         acc[ai][bj][m][n] = __builtin_amdgcn_mfma_f32_16x16x32_bf16(Bt[n][k], At[m][k], acc[ai][bj][m][n], 0, 0, 0); __builtin_amdgcn_s_setprio(0); } while (0)
; #define PG8_WAIT_V(n) asm volatile("s_waitcnt vmcnt(" #n ")" ::: "memory")
; #define PG8_WAIT_L(n) asm volatile("s_waitcnt lgkmcnt(" #n ")" ::: "memory")
; #define PG8_BAR __builtin_amdgcn_s_barrier()
; #define PG8_SCHED __builtin_amdgcn_sched_barrier(0)
; template <class Epi, class Sched>
; DI void gemm_phase(LAS unsigned char* lds, const Gemm g, const Sched& S, const Epi& E) {
;     ...
;             PG8_WAIT_V(8); PG8_WAIT_L(0); PG8_BAR; PG8_MMA(1, 0, At, B0); PG8_MMA(1, 1, At, B1); PG8_BAR; PG8_SCHED;
;             PG8_LDB(B0, 1, 0); PG8_LDB(B1, 1, 1); PG8_SCHED; PG8_LDA(At, 1, 0); PG8_STAGE(PG8_SA(0, 1), a2 + hstepA, voffA);
;             PG8_WAIT_V(8); PG8_WAIT_L(0); PG8_BAR; PG8_MMA(0, 0, At, B0); PG8_MMA(0, 1, At, B1); PG8_BAR; PG8_SCHED;
	s_waitcnt lgkmcnt(0)
	v_mfma_f32_16x16x32_bf16 v[76:79], v[56:59], v[170:173], v[76:79]
	v_mfma_f32_16x16x32_bf16 v[64:67], v[68:71], v[170:173], v[64:67]
	v_mfma_f32_16x16x32_bf16 v[44:47], v[56:59], v[178:181], v[44:47]
	v_mfma_f32_16x16x32_bf16 v[40:43], v[68:71], v[178:181], v[40:43]
	v_mfma_f32_16x16x32_bf16 v[28:31], v[56:59], v[186:189], v[28:31]
	v_mfma_f32_16x16x32_bf16 v[24:27], v[68:71], v[186:189], v[24:27]
	v_mfma_f32_16x16x32_bf16 v[12:15], v[56:59], v[194:197], v[12:15]
	v_mfma_f32_16x16x32_bf16 v[8:11], v[68:71], v[194:197], v[8:11]
	v_mfma_f32_16x16x32_bf16 v[76:79], v[60:63], v[174:177], v[76:79]
	v_mfma_f32_16x16x32_bf16 v[64:67], v[72:75], v[174:177], v[64:67]
	v_mfma_f32_16x16x32_bf16 v[44:47], v[60:63], v[182:185], v[44:47]
	v_mfma_f32_16x16x32_bf16 v[40:43], v[72:75], v[182:185], v[40:43]
	v_mfma_f32_16x16x32_bf16 v[28:31], v[60:63], v[190:193], v[28:31]
	v_mfma_f32_16x16x32_bf16 v[24:27], v[72:75], v[190:193], v[24:27]
	v_mfma_f32_16x16x32_bf16 v[12:15], v[60:63], v[198:201], v[12:15]
	v_mfma_f32_16x16x32_bf16 v[8:11], v[72:75], v[198:201], v[8:11]
	v_mfma_f32_16x16x32_bf16 v[52:55], v[144:147], v[170:173], v[52:55]
	v_mfma_f32_16x16x32_bf16 v[48:51], v[158:161], v[170:173], v[48:51]
	v_mfma_f32_16x16x32_bf16 v[36:39], v[144:147], v[178:181], v[36:39]
	v_mfma_f32_16x16x32_bf16 v[32:35], v[158:161], v[178:181], v[32:35]
	v_mfma_f32_16x16x32_bf16 v[20:23], v[144:147], v[186:189], v[20:23]
	v_mfma_f32_16x16x32_bf16 v[16:19], v[158:161], v[186:189], v[16:19]
	v_mfma_f32_16x16x32_bf16 v[4:7], v[144:147], v[194:197], v[4:7]
	v_mfma_f32_16x16x32_bf16 v[0:3], v[158:161], v[194:197], v[0:3]
	v_mfma_f32_16x16x32_bf16 v[52:55], v[148:151], v[174:177], v[52:55]
	v_mfma_f32_16x16x32_bf16 v[48:51], v[162:165], v[174:177], v[48:51]
	v_mfma_f32_16x16x32_bf16 v[36:39], v[148:151], v[182:185], v[36:39]
	v_mfma_f32_16x16x32_bf16 v[32:35], v[162:165], v[182:185], v[32:35]
	v_mfma_f32_16x16x32_bf16 v[20:23], v[148:151], v[190:193], v[20:23]
	v_mfma_f32_16x16x32_bf16 v[16:19], v[162:165], v[190:193], v[16:19]
	v_mfma_f32_16x16x32_bf16 v[4:7], v[148:151], v[198:201], v[4:7]
	v_mfma_f32_16x16x32_bf16 v[0:3], v[162:165], v[198:201], v[0:3]
	s_barrier
	s_add_i32 s9, 0, 0x18000
	s_add_i32 s12, 0, 0x1c000
	v_add_u32_e32 v72, s9, v167
	v_add_u32_e32 v162, s12, v167
	ds_read_b128 v[56:59], v72
	ds_read_b128 v[60:63], v72 offset:1024
	ds_read_b128 v[68:71], v72 offset:2048
	ds_read_b128 v[72:75], v72 offset:3072
	ds_read_b128 v[144:147], v162
	ds_read_b128 v[148:151], v162 offset:1024
	ds_read_b128 v[158:161], v162 offset:2048
	ds_read_b128 v[162:165], v162 offset:3072
	s_add_u32 s10, s70, 0x80000
	s_addc_u32 s11, s71, 0
	s_mov_b32 m0, s73
	v_lshl_add_u64 v[210:211], s[10:11], 0, v[222:223]
	ds_read_b128 v[170:173], v169 offset:32768
	ds_read_b128 v[174:177], v169 offset:33792
	ds_read_b128 v[178:181], v169 offset:34816
	ds_read_b128 v[182:185], v169 offset:35840
	ds_read_b128 v[186:189], v169 offset:36864
	ds_read_b128 v[190:193], v169 offset:37888
	ds_read_b128 v[194:197], v169 offset:38912
	ds_read_b128 v[198:201], v169 offset:39936
	global_load_lds_dwordx4 v[210:211], off
	v_lshl_add_u64 v[210:211], s[10:11], 0, v[152:153]
	s_mov_b32 m0, s74
	s_nop 0
	global_load_lds_dwordx4 v[210:211], off
	s_waitcnt vmcnt(8)
	s_waitcnt lgkmcnt(0)
	s_barrier
	s_waitcnt lgkmcnt(0)
	v_mfma_f32_16x16x32_bf16 v[140:143], v[56:59], v[170:173], v[140:143]
	v_mfma_f32_16x16x32_bf16 v[136:139], v[68:71], v[170:173], v[136:139]
	v_mfma_f32_16x16x32_bf16 v[124:127], v[56:59], v[178:181], v[124:127]
	v_mfma_f32_16x16x32_bf16 v[120:123], v[68:71], v[178:181], v[120:123]
	v_mfma_f32_16x16x32_bf16 v[108:111], v[56:59], v[186:189], v[108:111]
	v_mfma_f32_16x16x32_bf16 v[104:107], v[68:71], v[186:189], v[104:107]
	v_mfma_f32_16x16x32_bf16 v[92:95], v[56:59], v[194:197], v[92:95]
	v_mfma_f32_16x16x32_bf16 v[88:91], v[68:71], v[194:197], v[88:91]
	v_mfma_f32_16x16x32_bf16 v[140:143], v[60:63], v[174:177], v[140:143]
	v_mfma_f32_16x16x32_bf16 v[136:139], v[72:75], v[174:177], v[136:139]
	v_mfma_f32_16x16x32_bf16 v[124:127], v[60:63], v[182:185], v[124:127]
	v_mfma_f32_16x16x32_bf16 v[120:123], v[72:75], v[182:185], v[120:123]
	v_mfma_f32_16x16x32_bf16 v[108:111], v[60:63], v[190:193], v[108:111]
	v_mfma_f32_16x16x32_bf16 v[104:107], v[72:75], v[190:193], v[104:107]
	v_mfma_f32_16x16x32_bf16 v[92:95], v[60:63], v[198:201], v[92:95]
	v_mfma_f32_16x16x32_bf16 v[88:91], v[72:75], v[198:201], v[88:91]
	v_mfma_f32_16x16x32_bf16 v[132:135], v[144:147], v[170:173], v[132:135]
	v_mfma_f32_16x16x32_bf16 v[128:131], v[158:161], v[170:173], v[128:131]
	v_mfma_f32_16x16x32_bf16 v[116:119], v[144:147], v[178:181], v[116:119]
	v_mfma_f32_16x16x32_bf16 v[112:115], v[158:161], v[178:181], v[112:115]
	v_mfma_f32_16x16x32_bf16 v[100:103], v[144:147], v[186:189], v[100:103]
	v_mfma_f32_16x16x32_bf16 v[96:99], v[158:161], v[186:189], v[96:99]
	v_mfma_f32_16x16x32_bf16 v[84:87], v[144:147], v[194:197], v[84:87]
	v_mfma_f32_16x16x32_bf16 v[80:83], v[158:161], v[194:197], v[80:83]
	v_mfma_f32_16x16x32_bf16 v[132:135], v[148:151], v[174:177], v[132:135]
	v_mfma_f32_16x16x32_bf16 v[128:131], v[162:165], v[174:177], v[128:131]
	v_mfma_f32_16x16x32_bf16 v[116:119], v[148:151], v[182:185], v[116:119]
	v_mfma_f32_16x16x32_bf16 v[112:115], v[162:165], v[182:185], v[112:115]
	v_mfma_f32_16x16x32_bf16 v[100:103], v[148:151], v[190:193], v[100:103]
	v_mfma_f32_16x16x32_bf16 v[96:99], v[162:165], v[190:193], v[96:99]
	v_mfma_f32_16x16x32_bf16 v[84:87], v[148:151], v[198:201], v[84:87]
	v_mfma_f32_16x16x32_bf16 v[80:83], v[162:165], v[198:201], v[80:83]
	s_barrier
; #define PG8_STAGE(bufoff, gbase, voff) do { _Pragma("unroll") for (int _i = 0; _i < 2; ++_i) \
;         __builtin_amdgcn_global_load_lds((const unsigned*)((const char*)(gbase) + (voff)[_i]), (LAS unsigned*)(lds + (bufoff) + ldsw + _i * 8192), 16, 0, 0); } while (0)
; #define PG8_LDA(dst, b, h) do { _Pragma("unroll") for (int m = 0; m < 4; ++m) _Pragma("unroll") for (int k = 0; k < 2; ++k) dst[m][k] = *(const LAS bf16x8*)(lds + PG8_SA(b, h) + aoff + m * 2048 + k * 1024); } while (0)
; #define PG8_MMA(ai, bj, At, Bt) do { __builtin_amdgcn_s_setprio(1); _Pragma("unroll") for (int m = 0; m < 4; ++m) _Pragma("unroll") for (int n = 0; n < 2; ++n) _Pragma("unroll") for (int k = 0; k < 2; ++k) \
;         acc[ai][bj][m][n] = __builtin_amdgcn_mfma_f32_16x16x32_bf16(Bt[n][k], At[m][k], acc[ai][bj][m][n], 0, 0, 0); __builtin_amdgcn_s_setprio(0); } while (0)
; #define PG8_WAIT_V(n) asm volatile("s_waitcnt vmcnt(" #n ")" ::: "memory")
; #define PG8_WAIT_L(n) asm volatile("s_waitcnt lgkmcnt(" #n ")" ::: "memory")
; #define PG8_BAR __builtin_amdgcn_s_barrier()
; #define PG8_SCHED __builtin_amdgcn_sched_barrier(0)
; template <class Epi, class Sched>
; DI void gemm_phase(LAS unsigned char* lds, const Gemm g, const Sched& S, const Epi& E) {
;     ...
;             PG8_LDA(At, 1, 1); PG8_STAGE(PG8_SB(1, 0), b3, voffB); PG8_STAGE(PG8_SB(1, 1), b3 + hstepB, voffB); PG8_STAGE(PG8_SA(1, 0), a3, voffA);
;             PG8_WAIT_V(8); PG8_WAIT_L(0); PG8_BAR; PG8_MMA(1, 0, At, B0); PG8_MMA(1, 1, At, B1); PG8_BAR; PG8_SCHED;
;         }
;         if (wr == 0) PG8_BAR;
	s_add_i32 s9, s9, s4
	v_lshl_add_u64 v[202:203], v[202:203], 0, s[28:29]
	s_mov_b32 m0, s9
	ds_read_b128 v[170:173], v169 offset:49152
	ds_read_b128 v[174:177], v169 offset:50176
	ds_read_b128 v[178:181], v169 offset:51200
	ds_read_b128 v[182:185], v169 offset:52224
	ds_read_b128 v[186:189], v169 offset:53248
	ds_read_b128 v[190:193], v169 offset:54272
	ds_read_b128 v[194:197], v169 offset:55296
	ds_read_b128 v[198:201], v169 offset:56320
	global_load_lds_dwordx4 v[202:203], off
	s_add_i32 m0, s9, 0x2000
	s_add_u32 s10, s68, 0x80080
	v_lshl_add_u64 v[202:203], v[204:205], 0, s[28:29]
	s_addc_u32 s11, s69, 0
	s_add_i32 s9, s12, s4
	global_load_lds_dwordx4 v[202:203], off
	v_lshl_add_u64 v[202:203], s[10:11], 0, v[222:223]
	s_mov_b32 m0, s9
	s_nop 0
	global_load_lds_dwordx4 v[202:203], off
	v_lshl_add_u64 v[202:203], s[10:11], 0, v[152:153]
	s_add_i32 m0, s9, 0x2000
	s_nop 0
	global_load_lds_dwordx4 v[202:203], off
	v_lshl_add_u64 v[202:203], v[206:207], 0, s[28:29]
	s_mov_b32 m0, s75
	s_nop 0
	global_load_lds_dwordx4 v[202:203], off
	v_lshl_add_u64 v[202:203], v[208:209], 0, s[28:29]
	s_mov_b32 m0, s89
	s_nop 0
	global_load_lds_dwordx4 v[202:203], off
	s_waitcnt vmcnt(8)
	s_waitcnt lgkmcnt(0)
	s_barrier
	s_waitcnt lgkmcnt(0)
	v_mfma_f32_16x16x32_bf16 v[76:79], v[56:59], v[170:173], v[76:79]
	v_mfma_f32_16x16x32_bf16 v[64:67], v[68:71], v[170:173], v[64:67]
	v_mfma_f32_16x16x32_bf16 v[44:47], v[56:59], v[178:181], v[44:47]
	v_mfma_f32_16x16x32_bf16 v[40:43], v[68:71], v[178:181], v[40:43]
	v_mfma_f32_16x16x32_bf16 v[28:31], v[56:59], v[186:189], v[28:31]
	v_mfma_f32_16x16x32_bf16 v[24:27], v[68:71], v[186:189], v[24:27]
	v_mfma_f32_16x16x32_bf16 v[12:15], v[56:59], v[194:197], v[12:15]
	v_mfma_f32_16x16x32_bf16 v[8:11], v[68:71], v[194:197], v[8:11]
	v_mfma_f32_16x16x32_bf16 v[76:79], v[60:63], v[174:177], v[76:79]
	v_mfma_f32_16x16x32_bf16 v[64:67], v[72:75], v[174:177], v[64:67]
	v_mfma_f32_16x16x32_bf16 v[44:47], v[60:63], v[182:185], v[44:47]
	v_mfma_f32_16x16x32_bf16 v[40:43], v[72:75], v[182:185], v[40:43]
	v_mfma_f32_16x16x32_bf16 v[28:31], v[60:63], v[190:193], v[28:31]
	v_mfma_f32_16x16x32_bf16 v[24:27], v[72:75], v[190:193], v[24:27]
	v_mfma_f32_16x16x32_bf16 v[12:15], v[60:63], v[198:201], v[12:15]
	v_mfma_f32_16x16x32_bf16 v[8:11], v[72:75], v[198:201], v[8:11]
	v_mfma_f32_16x16x32_bf16 v[52:55], v[144:147], v[170:173], v[52:55]
	v_mfma_f32_16x16x32_bf16 v[48:51], v[158:161], v[170:173], v[48:51]
	v_mfma_f32_16x16x32_bf16 v[36:39], v[144:147], v[178:181], v[36:39]
	v_mfma_f32_16x16x32_bf16 v[32:35], v[158:161], v[178:181], v[32:35]
	v_mfma_f32_16x16x32_bf16 v[20:23], v[144:147], v[186:189], v[20:23]
	v_mfma_f32_16x16x32_bf16 v[16:19], v[158:161], v[186:189], v[16:19]
	v_mfma_f32_16x16x32_bf16 v[4:7], v[144:147], v[194:197], v[4:7]
	v_mfma_f32_16x16x32_bf16 v[0:3], v[158:161], v[194:197], v[0:3]
	v_mfma_f32_16x16x32_bf16 v[52:55], v[148:151], v[174:177], v[52:55]
	v_mfma_f32_16x16x32_bf16 v[48:51], v[162:165], v[174:177], v[48:51]
	v_mfma_f32_16x16x32_bf16 v[36:39], v[148:151], v[182:185], v[36:39]
	v_mfma_f32_16x16x32_bf16 v[32:35], v[162:165], v[182:185], v[32:35]
	v_mfma_f32_16x16x32_bf16 v[20:23], v[148:151], v[190:193], v[20:23]
	v_mfma_f32_16x16x32_bf16 v[16:19], v[162:165], v[190:193], v[16:19]
	v_mfma_f32_16x16x32_bf16 v[4:7], v[148:151], v[198:201], v[4:7]
	v_mfma_f32_16x16x32_bf16 v[0:3], v[162:165], v[198:201], v[0:3]
	s_barrier
	s_add_i32 s8, s8, 2
	s_add_u32 s66, s66, 0x100
	s_addc_u32 s67, s67, 0
	s_add_u32 s6, s6, 0x100
	s_addc_u32 s7, s7, 0
	s_cmp_gt_u32 s8, 29
	s_cbranch_scc0 .LBB0_417
	s_and_b64 vcc, exec, s[18:19]
	s_cbranch_vccz .LBB0_420
	s_barrier
